# attention unit epilogue: 8 global_store_dwordx2 -> 4 global_store_dwordx4 via v_permlane32_swap pairs (docs 7.3/T21), both layers; same bytes/addresses
# speedup vs baseline: 1.0059x; 1.0059x over previous
; __device__ __forceinline__ float bflo(unsigned w) { return __uint_as_float(w << 16); }
; __device__ __forceinline__ float bfhi(unsigned w) { return __uint_as_float(w & 0xffff0000u); }
; __device__ __forceinline__ unsigned pk2(float lo, float hi) { const f32x2n v = {lo, hi}; return __builtin_bit_cast(unsigned, __builtin_convertvector(v, bf16x2n)); }
; __device__ __forceinline__ void attn_phase_mfma(const Ctx& c, unsigned char* lds_raw, bool do_store) {
;     ...
;         {
;             const u32x4 q0 = qn[0], q1 = qn[1], q2 = qn[2], q3 = qn[3];
;             const h16x8 cav = tq[0], cbv = tq[1], sav = tq[2], sbv = tq[3];
;             const float sc = 0.125f * 1.44269504f;
;             u32x4 o0, o1, o2, o3;
;     #pragma unroll
;             for (int e = 0; e < 4; ++e) {
;                 const float ca_0 = (float)cav[2 * e], ca_1 = (float)cav[2 * e + 1], sa_0 = (float)sav[2 * e], sa_1 = (float)sav[2 * e + 1];
;                 const float cb_0 = (float)cbv[2 * e], cb_1 = (float)cbv[2 * e + 1], sb_0 = (float)sbv[2 * e], sb_1 = (float)sbv[2 * e + 1];
;                 const float a0 = bflo(q0[e]), a1 = bfhi(q0[e]), b0 = bflo(q2[e]), b1 = bfhi(q2[e]);
;                 const float e0 = bflo(q1[e]), e1 = bfhi(q1[e]), f0 = bflo(q3[e]), f1 = bfhi(q3[e]);
;                 o0[e] = pk2((a0 * ca_0 - b0 * sa_0) * sc, (a1 * ca_1 - b1 * sa_1) * sc);
;                 o2[e] = pk2((b0 * ca_0 + a0 * sa_0) * sc, (b1 * ca_1 + a1 * sa_1) * sc);
;                 o1[e] = pk2((e0 * cb_0 - f0 * sb_0) * sc, (e1 * cb_1 - f1 * sb_1) * sc);
;                 o3[e] = pk2((f0 * cb_0 + e0 * sb_0) * sc, (f1 * cb_1 + e1 * sb_1) * sc);
;             }
;             qf[0] = __builtin_bit_cast(bf16x8, o0); qf[1] = __builtin_bit_cast(bf16x8, o1); qf[2] = __builtin_bit_cast(bf16x8, o2); qf[3] = __builtin_bit_cast(bf16x8, o3);
;         }
.LBB0_379:
	s_bfe_u32 s2, s91, 0x20004
	s_ashr_i32 s91, s90, 31
	s_lshl_b64 s[0:1], s[90:91], 12
	v_ashrrev_i32_e32 v59, 31, v58
	v_lshl_add_u64 v[108:109], s[0:1], 0, v[58:59]
	v_mov_b64_e32 v[34:35], s[92:93]
	v_cvt_f32_f16_sdwa v37, v26 dst_sel:DWORD dst_unused:UNUSED_PAD src0_sel:WORD_1
	v_cvt_f32_f16_e32 v36, v26
	v_mad_u64_u32 v[174:175], s[0:1], v108, s8, v[34:35]
	v_cvt_f32_f16_sdwa v35, v30 dst_sel:DWORD dst_unused:UNUSED_PAD src0_sel:WORD_1
	v_cvt_f32_f16_e32 v34, v30
	v_lshlrev_b32_e32 v38, 16, v10
	v_and_b32_e32 v39, 0xffff0000, v10
	v_lshlrev_b32_e32 v40, 16, v14
	v_and_b32_e32 v41, 0xffff0000, v14
	v_pk_mul_f32 v[42:43], v[40:41], v[36:37]
	v_pk_mul_f32 v[36:37], v[38:39], v[36:37]
	v_pk_fma_f32 v[42:43], v[38:39], v[34:35], v[42:43] neg_lo:[0,0,1] neg_hi:[0,0,1]
	v_pk_fma_f32 v[34:35], v[40:41], v[34:35], v[36:37]
	v_cvt_f32_f16_sdwa v37, v18 dst_sel:DWORD dst_unused:UNUSED_PAD src0_sel:WORD_1
	v_pk_mul_f32 v[34:35], v[34:35], s[72:73] op_sel_hi:[1,0]
	v_cvt_f32_f16_e32 v36, v18
	v_cvt_pk_bf16_f32 v150, v34, v35
	v_cvt_f32_f16_sdwa v35, v22 dst_sel:DWORD dst_unused:UNUSED_PAD src0_sel:WORD_1
	v_cvt_f32_f16_e32 v34, v22
	v_pk_mul_f32 v[42:43], v[42:43], s[72:73] op_sel_hi:[1,0]
	v_lshlrev_b32_e32 v38, 16, v2
	v_and_b32_e32 v39, 0xffff0000, v2
	v_lshlrev_b32_e32 v40, 16, v6
	v_and_b32_e32 v41, 0xffff0000, v6
	v_cvt_pk_bf16_f32 v224, v42, v43
	v_pk_mul_f32 v[42:43], v[40:41], v[36:37]
	v_pk_mul_f32 v[36:37], v[38:39], v[36:37]
	v_pk_fma_f32 v[42:43], v[38:39], v[34:35], v[42:43] neg_lo:[0,0,1] neg_hi:[0,0,1]
	v_pk_fma_f32 v[34:35], v[40:41], v[34:35], v[36:37]
	v_cvt_f32_f16_e32 v30, v27
	v_pk_mul_f32 v[34:35], v[34:35], s[72:73] op_sel_hi:[1,0]
	v_lshlrev_b32_e32 v14, 16, v15
	v_cvt_pk_bf16_f32 v154, v34, v35
	v_cvt_f32_f16_sdwa v35, v31 dst_sel:DWORD dst_unused:UNUSED_PAD src0_sel:WORD_1
	v_cvt_f32_f16_e32 v34, v31
	v_cvt_f32_f16_sdwa v31, v27 dst_sel:DWORD dst_unused:UNUSED_PAD src0_sel:WORD_1
	v_and_b32_e32 v15, 0xffff0000, v15
	v_lshlrev_b32_e32 v10, 16, v11
	v_and_b32_e32 v11, 0xffff0000, v11
	v_pk_mul_f32 v[26:27], v[14:15], v[30:31]
	v_lshlrev_b32_e32 v6, 16, v7
	v_pk_fma_f32 v[26:27], v[10:11], v[34:35], v[26:27] neg_lo:[0,0,1] neg_hi:[0,0,1]
	v_pk_mul_f32 v[10:11], v[10:11], v[30:31]
	v_and_b32_e32 v7, 0xffff0000, v7
	v_pk_fma_f32 v[10:11], v[14:15], v[34:35], v[10:11]
	v_cvt_f32_f16_sdwa v15, v19 dst_sel:DWORD dst_unused:UNUSED_PAD src0_sel:WORD_1
	v_pk_mul_f32 v[10:11], v[10:11], s[72:73] op_sel_hi:[1,0]
	v_cvt_f32_f16_e32 v14, v19
	v_cvt_pk_bf16_f32 v151, v10, v11
	v_cvt_f32_f16_sdwa v11, v23 dst_sel:DWORD dst_unused:UNUSED_PAD src0_sel:WORD_1
	v_cvt_f32_f16_e32 v10, v23
	v_lshlrev_b32_e32 v2, 16, v3
	v_and_b32_e32 v3, 0xffff0000, v3
	v_pk_mul_f32 v[18:19], v[6:7], v[14:15]
	v_pk_mul_f32 v[26:27], v[26:27], s[72:73] op_sel_hi:[1,0]
	v_pk_fma_f32 v[18:19], v[2:3], v[10:11], v[18:19] neg_lo:[0,0,1] neg_hi:[0,0,1]
	v_pk_mul_f32 v[2:3], v[2:3], v[14:15]
	v_pk_mul_f32 v[18:19], v[18:19], s[72:73] op_sel_hi:[1,0]
	v_pk_fma_f32 v[2:3], v[6:7], v[10:11], v[2:3]
	v_cvt_f32_f16_sdwa v7, v28 dst_sel:DWORD dst_unused:UNUSED_PAD src0_sel:WORD_1
	v_pk_mul_f32 v[2:3], v[2:3], s[72:73] op_sel_hi:[1,0]
	v_cvt_f32_f16_e32 v6, v28
	v_cvt_pk_bf16_f32 v155, v2, v3
	v_cvt_f32_f16_sdwa v3, v32 dst_sel:DWORD dst_unused:UNUSED_PAD src0_sel:WORD_1
	v_cvt_f32_f16_e32 v2, v32
	v_lshlrev_b32_e32 v14, 16, v16
	v_and_b32_e32 v15, 0xffff0000, v16
	v_cvt_pk_bf16_f32 v229, v18, v19
	v_lshlrev_b32_e32 v10, 16, v12
	v_and_b32_e32 v11, 0xffff0000, v12
	v_pk_mul_f32 v[18:19], v[14:15], v[6:7]
	v_cvt_pk_bf16_f32 v225, v26, v27
	v_pk_fma_f32 v[18:19], v[10:11], v[2:3], v[18:19] neg_lo:[0,0,1] neg_hi:[0,0,1]
	v_cvt_f32_f16_sdwa v23, v29 dst_sel:DWORD dst_unused:UNUSED_PAD src0_sel:WORD_1
	v_cvt_f32_f16_e32 v22, v29
	ds_read_b128 v[26:29], v216
	v_pk_mul_f32 v[18:19], v[18:19], s[72:73] op_sel_hi:[1,0]
	v_lshlrev_b32_e32 v16, 16, v17
	v_cvt_pk_bf16_f32 v226, v18, v19
	v_cvt_f32_f16_sdwa v19, v33 dst_sel:DWORD dst_unused:UNUSED_PAD src0_sel:WORD_1
	v_cvt_f32_f16_e32 v18, v33
	v_and_b32_e32 v17, 0xffff0000, v17
	v_pk_mul_f32 v[6:7], v[10:11], v[6:7]
	v_lshlrev_b32_e32 v30, 16, v13
	v_and_b32_e32 v31, 0xffff0000, v13
	v_pk_mul_f32 v[10:11], v[16:17], v[22:23]
	v_pk_fma_f32 v[2:3], v[14:15], v[2:3], v[6:7]
	v_pk_fma_f32 v[10:11], v[30:31], v[18:19], v[10:11] neg_lo:[0,0,1] neg_hi:[0,0,1]
	v_pk_mul_f32 v[42:43], v[42:43], s[72:73] op_sel_hi:[1,0]
	v_pk_mul_f32 v[10:11], v[10:11], s[72:73] op_sel_hi:[1,0]
	v_pk_mul_f32 v[2:3], v[2:3], s[72:73] op_sel_hi:[1,0]
	v_cvt_pk_bf16_f32 v227, v10, v11
	v_cvt_f32_f16_sdwa v7, v20 dst_sel:DWORD dst_unused:UNUSED_PAD src0_sel:WORD_1
	v_cvt_f32_f16_e32 v6, v20
	s_waitcnt lgkmcnt(0)
	v_mfma_f32_32x32x16_bf16 v[66:81], v[26:29], v[224:227], 0
	ds_read_b128 v[10:13], v216 offset:4096
	v_cvt_pk_bf16_f32 v228, v42, v43
	v_cvt_pk_bf16_f32 v152, v2, v3
	v_cvt_f32_f16_sdwa v3, v24 dst_sel:DWORD dst_unused:UNUSED_PAD src0_sel:WORD_1
	v_cvt_f32_f16_e32 v2, v24
	v_lshlrev_b32_e32 v14, 16, v4
	s_waitcnt lgkmcnt(0)
	v_mfma_f32_32x32x16_bf16 v[50:65], v[10:13], v[224:227], 0
	ds_read_b128 v[10:13], v216 offset:8192
	v_and_b32_e32 v15, 0xffff0000, v4
	v_lshlrev_b32_e32 v26, 16, v8
	v_and_b32_e32 v27, 0xffff0000, v8
	v_pk_mul_f32 v[28:29], v[26:27], v[6:7]
	v_pk_mul_f32 v[6:7], v[14:15], v[6:7]
	s_waitcnt lgkmcnt(0)
; #define LASP __attribute__((address_space(3)))
; __device__ __forceinline__ void attn_phase_mfma(const Ctx& c, unsigned char* lds_raw, bool do_store) {
;     ...
;         for (int kb = 0; kb < 5; ++kb)
;     #pragma unroll
;             for (int e = 0; e < 16; ++e) sacc[kb][e] = 0.f;
;     #pragma unroll
;         for (int s4 = 0; s4 < 4; ++s4) {
;     #pragma unroll
;             for (int kb = 0; kb < 5; ++kb) {
;                 const int row = 32 * wave + 32 * kb + rq;
;                 const bf16x8 kf = *(const LASP bf16x8*)(Kt + row * 128 + (((2 * s4 + h) ^ (row & 7)) << 4));
;                 sacc[kb] = mfma32_g(kf, qf[s4], sacc[kb]);
;             }
;             __builtin_amdgcn_sched_barrier(0);
;         }
;         asm volatile("s_nop 15\n\ts_nop 15" : "+v"(sacc[0]), "+v"(sacc[1]), "+v"(sacc[2]), "+v"(sacc[3]), "+v"(sacc[4]));
;         const int jbase = i0 - 64 + 32 * wave;
;         float mx = -1e30f;
;     #pragma unroll
;         for (int kb = 0; kb < 5; ++kb)
;     #pragma unroll
;             for (int e = 0; e < 16; ++e) {
;                 const int row = (e & 3) + 8 * (e >> 2) + 4 * h, rel = 32 * kb + row - rq, j = jbase + 32 * kb + row;
;                 const bool valid = (rel >= 0) && (rel <= 128) && (j >= 0) && (j < L);
;                 const float sv = valid ? sacc[kb][e] : -1e30f;
;                 sacc[kb][e] = sv; mx = fmaxf(mx, sv);
	v_mfma_f32_32x32x16_bf16 v[34:49], v[10:13], v[224:227], 0
	ds_read_b128 v[10:13], v216 offset:12288
	v_pk_fma_f32 v[28:29], v[14:15], v[2:3], v[28:29] neg_lo:[0,0,1] neg_hi:[0,0,1]
	v_pk_fma_f32 v[2:3], v[26:27], v[2:3], v[6:7]
	v_pk_mul_f32 v[28:29], v[28:29], s[72:73] op_sel_hi:[1,0]
	v_pk_mul_f32 v[2:3], v[2:3], s[72:73] op_sel_hi:[1,0]
	v_cvt_pk_bf16_f32 v230, v28, v29
	v_cvt_pk_bf16_f32 v156, v2, v3
	v_pk_mul_f32 v[2:3], v[30:31], v[22:23]
	v_cvt_f32_f16_sdwa v7, v21 dst_sel:DWORD dst_unused:UNUSED_PAD src0_sel:WORD_1
	v_pk_fma_f32 v[2:3], v[16:17], v[18:19], v[2:3]
	v_cvt_f32_f16_e32 v6, v21
	v_pk_mul_f32 v[2:3], v[2:3], s[72:73] op_sel_hi:[1,0]
	v_lshlrev_b32_e32 v8, 16, v9
	v_cvt_pk_bf16_f32 v153, v2, v3
	v_cvt_f32_f16_sdwa v3, v25 dst_sel:DWORD dst_unused:UNUSED_PAD src0_sel:WORD_1
	v_cvt_f32_f16_e32 v2, v25
	s_waitcnt lgkmcnt(0)
	v_mfma_f32_32x32x16_bf16 v[18:33], v[10:13], v[224:227], 0
	ds_read_b128 v[232:235], v216 offset:16384
	v_and_b32_e32 v9, 0xffff0000, v9
	v_lshlrev_b32_e32 v4, 16, v5
	v_and_b32_e32 v5, 0xffff0000, v5
	v_pk_mul_f32 v[14:15], v[8:9], v[6:7]
	s_lshl_b32 s0, s88, 8
	s_lshl_b32 s1, s2, 6
	v_pk_fma_f32 v[14:15], v[4:5], v[2:3], v[14:15] neg_lo:[0,0,1] neg_hi:[0,0,1]
	v_pk_mul_f32 v[4:5], v[4:5], v[6:7]
	s_or_b32 s0, s1, s0
	v_pk_fma_f32 v[2:3], v[8:9], v[2:3], v[4:5]
	v_mad_i32_i24 v175, v109, s8, v175
	s_ashr_i32 s1, s0, 31
	v_pk_mul_f32 v[10:11], v[14:15], s[72:73] op_sel_hi:[1,0]
	v_pk_mul_f32 v[2:3], v[2:3], s[72:73] op_sel_hi:[1,0]
	v_cvt_pk_bf16_f32 v231, v10, v11
	v_cvt_pk_bf16_f32 v157, v2, v3
	s_lshr_b32 s3, 0x1000, s96
	v_lshl_add_u64 v[174:175], s[0:1], 1, v[174:175]
	s_waitcnt lgkmcnt(0)
	v_mfma_f32_32x32x16_bf16 v[2:17], v[232:235], v[224:227], 0
	ds_read_b128 v[224:227], v217
	s_waitcnt lgkmcnt(0)
	v_mfma_f32_32x32x16_bf16 v[66:81], v[224:227], v[228:231], v[66:81]
	ds_read_b128 v[224:227], v217 offset:4096
	s_waitcnt lgkmcnt(0)
	v_mfma_f32_32x32x16_bf16 v[50:65], v[224:227], v[228:231], v[50:65]
	ds_read_b128 v[224:227], v217 offset:8192
	s_waitcnt lgkmcnt(0)
	v_mfma_f32_32x32x16_bf16 v[34:49], v[224:227], v[228:231], v[34:49]
	ds_read_b128 v[224:227], v217 offset:12288
	s_waitcnt lgkmcnt(0)
	v_mfma_f32_32x32x16_bf16 v[18:33], v[224:227], v[228:231], v[18:33]
	ds_read_b128 v[224:227], v217 offset:16384
	s_waitcnt lgkmcnt(0)
	v_mfma_f32_32x32x16_bf16 v[2:17], v[224:227], v[228:231], v[2:17]
	ds_read_b128 v[224:227], v218
	s_waitcnt lgkmcnt(0)
	v_mfma_f32_32x32x16_bf16 v[66:81], v[224:227], v[150:153], v[66:81]
	ds_read_b128 v[224:227], v218 offset:4096
	s_waitcnt lgkmcnt(0)
	v_mfma_f32_32x32x16_bf16 v[50:65], v[224:227], v[150:153], v[50:65]
	ds_read_b128 v[224:227], v218 offset:8192
	s_waitcnt lgkmcnt(0)
	v_mfma_f32_32x32x16_bf16 v[34:49], v[224:227], v[150:153], v[34:49]
	ds_read_b128 v[224:227], v218 offset:12288
	s_waitcnt lgkmcnt(0)
	v_mfma_f32_32x32x16_bf16 v[18:33], v[224:227], v[150:153], v[18:33]
	ds_read_b128 v[224:227], v218 offset:16384
	s_waitcnt lgkmcnt(0)
	v_mfma_f32_32x32x16_bf16 v[2:17], v[224:227], v[150:153], v[2:17]
	ds_read_b128 v[150:153], v219
	s_waitcnt lgkmcnt(0)
	v_mfma_f32_32x32x16_bf16 v[66:81], v[150:153], v[154:157], v[66:81]
	ds_read_b128 v[150:153], v219 offset:4096
	s_waitcnt lgkmcnt(0)
	v_mfma_f32_32x32x16_bf16 v[50:65], v[150:153], v[154:157], v[50:65]
	ds_read_b128 v[150:153], v219 offset:8192
	s_waitcnt lgkmcnt(0)
	v_mfma_f32_32x32x16_bf16 v[34:49], v[150:153], v[154:157], v[34:49]
	ds_read_b128 v[150:153], v219 offset:12288
	s_waitcnt lgkmcnt(0)
	v_mfma_f32_32x32x16_bf16 v[18:33], v[150:153], v[154:157], v[18:33]
	ds_read_b128 v[150:153], v219 offset:16384
	s_waitcnt lgkmcnt(0)
	v_mfma_f32_32x32x16_bf16 v[2:17], v[150:153], v[154:157], v[2:17]
	s_add_i32 s0, s89, s73
	s_cmp_gt_i32 s0, -1
	v_readlane_b32 s12, v255, 17
	s_cselect_b64 s[10:11], -1, 0
	v_or_b32_e32 v107, s0, v166
	v_readlane_b32 s13, v255, 18
	s_and_b64 s[12:13], s[12:13], s[10:11]
	v_cmp_gt_i32_e32 vcc, s3, v107
	s_nop 15
	s_nop 15
	s_and_b64 vcc, s[12:13], vcc
	v_readlane_b32 s12, v255, 19
	v_cndmask_b32_e32 v107, v222, v66, vcc
	v_or_b32_e32 v66, s0, v184
	v_readlane_b32 s13, v255, 20
	s_and_b64 s[12:13], s[12:13], s[10:11]
	v_cmp_gt_i32_e32 vcc, s3, v66
	s_and_b64 vcc, s[12:13], vcc
	v_readlane_b32 s12, v255, 21
	v_or_b32_e32 v150, s0, v185
	v_readlane_b32 s13, v255, 22
	v_cndmask_b32_e32 v67, v222, v67, vcc
	s_and_b64 s[12:13], s[12:13], s[10:11]
	v_cmp_gt_i32_e32 vcc, s3, v150
	s_and_b64 vcc, s[12:13], vcc
	v_readlane_b32 s12, v255, 23
	v_or_b32_e32 v150, s0, v186
	v_readlane_b32 s13, v255, 24
	v_cndmask_b32_e32 v68, v222, v68, vcc
	s_and_b64 s[12:13], s[12:13], s[10:11]
	v_cmp_gt_i32_e32 vcc, s3, v150
	s_and_b64 vcc, s[12:13], vcc
	v_or_b32_e32 v150, s0, v187
	v_cndmask_b32_e32 v69, v222, v69, vcc
	s_and_b64 s[12:13], s[14:15], s[10:11]
	v_cmp_gt_i32_e32 vcc, s3, v150
	s_and_b64 vcc, s[12:13], vcc
	v_or_b32_e32 v150, s0, v188
	v_cndmask_b32_e32 v70, v222, v70, vcc
	s_and_b64 s[12:13], s[16:17], s[10:11]
	v_cmp_gt_i32_e32 vcc, s3, v150
	s_and_b64 vcc, s[12:13], vcc
	v_or_b32_e32 v150, s0, v189
	v_cndmask_b32_e32 v71, v222, v71, vcc
	s_and_b64 s[12:13], s[18:19], s[10:11]
	v_cmp_gt_i32_e32 vcc, s3, v150
	s_and_b64 vcc, s[12:13], vcc
	v_or_b32_e32 v150, s0, v190
	v_cndmask_b32_e32 v72, v222, v72, vcc
	s_and_b64 s[12:13], s[20:21], s[10:11]
	v_cmp_gt_i32_e32 vcc, s3, v150
	s_and_b64 vcc, s[12:13], vcc
	v_or_b32_e32 v150, s0, v191
	v_cndmask_b32_e32 v73, v222, v73, vcc
	s_and_b64 s[12:13], s[22:23], s[10:11]
	v_cmp_gt_i32_e32 vcc, s3, v150
	s_and_b64 vcc, s[12:13], vcc
	v_or_b32_e32 v150, s0, v192
	v_cndmask_b32_e32 v74, v222, v74, vcc
	s_and_b64 s[12:13], s[24:25], s[10:11]
; __device__ __forceinline__ void attn_phase_mfma(const Ctx& c, unsigned char* lds_raw, bool do_store) {
;     ...
;         const int jbase = i0 - 64 + 32 * wave;
;         float mx = -1e30f;
;     #pragma unroll
;         for (int kb = 0; kb < 5; ++kb)
;     #pragma unroll
;             for (int e = 0; e < 16; ++e) {
;                 const int row = (e & 3) + 8 * (e >> 2) + 4 * h, rel = 32 * kb + row - rq, j = jbase + 32 * kb + row;
;                 const bool valid = (rel >= 0) && (rel <= 128) && (j >= 0) && (j < L);
;                 const float sv = valid ? sacc[kb][e] : -1e30f;
;                 sacc[kb][e] = sv; mx = fmaxf(mx, sv);
;             }
	v_cmp_gt_i32_e32 vcc, s3, v150
	s_and_b64 vcc, s[12:13], vcc
	v_or_b32_e32 v150, s0, v193
	v_cndmask_b32_e32 v75, v222, v75, vcc
	s_and_b64 s[12:13], s[26:27], s[10:11]
	v_cmp_gt_i32_e32 vcc, s3, v150
	s_and_b64 vcc, s[12:13], vcc
	v_or_b32_e32 v150, s0, v194
	v_cndmask_b32_e32 v76, v222, v76, vcc
	s_and_b64 s[12:13], s[28:29], s[10:11]
	v_cmp_gt_i32_e32 vcc, s3, v150
	s_and_b64 vcc, s[12:13], vcc
	v_or_b32_e32 v150, s0, v195
	v_cndmask_b32_e32 v77, v222, v77, vcc
	s_and_b64 s[12:13], s[30:31], s[10:11]
	v_cmp_gt_i32_e32 vcc, s3, v150
	s_and_b64 vcc, s[12:13], vcc
	v_or_b32_e32 v150, s0, v196
	v_cndmask_b32_e32 v78, v222, v78, vcc
	s_and_b64 s[12:13], s[34:35], s[10:11]
	v_cmp_gt_i32_e32 vcc, s3, v150
	s_and_b64 vcc, s[12:13], vcc
	v_or_b32_e32 v150, s0, v197
	v_cndmask_b32_e32 v79, v222, v79, vcc
	s_and_b64 s[12:13], s[36:37], s[10:11]
	v_cmp_gt_i32_e32 vcc, s3, v150
	s_and_b64 vcc, s[12:13], vcc
	v_or_b32_e32 v150, s0, v198
	s_mov_b32 s1, 0xf149f2ca
	v_cndmask_b32_e32 v80, v222, v80, vcc
	s_and_b64 s[10:11], s[38:39], s[10:11]
	v_cmp_gt_i32_e32 vcc, s3, v150
	v_max3_f32 v66, v107, s1, v67
	s_and_b64 vcc, s[10:11], vcc
	s_add_i32 s1, s0, 32
	s_cmpk_gt_i32 s0, 0xffdf
	v_or_b32_e32 v150, s1, v166
	v_cndmask_b32_e32 v81, v222, v81, vcc
	s_cselect_b64 s[10:11], -1, 0
	v_cmp_gt_i32_e32 vcc, s3, v150
	s_and_b64 vcc, s[10:11], vcc
	s_add_i32 s9, s9, s73
	v_cndmask_b32_e32 v150, v222, v50, vcc
	v_or_b32_e32 v50, s1, v184
	v_cmp_gt_i32_e32 vcc, s3, v50
	s_and_b64 vcc, s[10:11], vcc
	v_max3_f32 v66, v66, v68, v69
	v_cndmask_b32_e32 v151, v222, v51, vcc
	v_or_b32_e32 v51, s1, v185
	v_cmp_gt_i32_e32 vcc, s3, v51
	s_and_b64 vcc, s[10:11], vcc
	v_or_b32_e32 v51, s1, v186
	v_cndmask_b32_e32 v152, v222, v52, vcc
	v_cmp_gt_i32_e32 vcc, s3, v51
	s_and_b64 vcc, s[10:11], vcc
	v_or_b32_e32 v51, s1, v187
	v_cndmask_b32_e32 v153, v222, v53, vcc
	v_cmp_gt_i32_e32 vcc, s3, v51
	s_and_b64 vcc, s[10:11], vcc
	v_or_b32_e32 v51, s1, v188
	v_cndmask_b32_e32 v154, v222, v54, vcc
	v_cmp_gt_i32_e32 vcc, s3, v51
	s_and_b64 vcc, s[10:11], vcc
	v_or_b32_e32 v51, s1, v189
	v_cndmask_b32_e32 v155, v222, v55, vcc
	v_cmp_gt_i32_e32 vcc, s3, v51
	s_and_b64 vcc, s[10:11], vcc
	v_or_b32_e32 v51, s1, v190
	v_cndmask_b32_e32 v156, v222, v56, vcc
	v_cmp_gt_i32_e32 vcc, s3, v51
	s_and_b64 vcc, s[10:11], vcc
	v_or_b32_e32 v51, s1, v191
	v_cndmask_b32_e32 v157, v222, v57, vcc
	v_cmp_gt_i32_e32 vcc, s3, v51
	s_and_b64 vcc, s[10:11], vcc
	v_or_b32_e32 v51, s1, v192
	v_cndmask_b32_e32 v159, v222, v58, vcc
	v_cmp_gt_i32_e32 vcc, s3, v51
	s_and_b64 vcc, s[10:11], vcc
	v_or_b32_e32 v51, s1, v193
	v_cndmask_b32_e32 v169, v222, v59, vcc
	v_cmp_gt_i32_e32 vcc, s3, v51
	s_and_b64 vcc, s[10:11], vcc
	v_or_b32_e32 v51, s1, v194
	v_cndmask_b32_e32 v224, v222, v60, vcc
	v_cmp_gt_i32_e32 vcc, s3, v51
	s_and_b64 vcc, s[10:11], vcc
	v_or_b32_e32 v51, s1, v195
	v_cndmask_b32_e32 v225, v222, v61, vcc
	v_cmp_gt_i32_e32 vcc, s3, v51
	s_and_b64 vcc, s[10:11], vcc
	v_or_b32_e32 v51, s1, v196
	v_cndmask_b32_e32 v226, v222, v62, vcc
	v_cmp_gt_i32_e32 vcc, s3, v51
	s_and_b64 vcc, s[10:11], vcc
	v_or_b32_e32 v51, s1, v197
	v_cndmask_b32_e32 v227, v222, v63, vcc
	v_cmp_gt_i32_e32 vcc, s3, v51
	s_and_b64 vcc, s[10:11], vcc
	v_or_b32_e32 v51, s1, v198
	v_cndmask_b32_e32 v228, v222, v64, vcc
	v_cmp_gt_i32_e32 vcc, s3, v51
	s_and_b64 vcc, s[10:11], vcc
	s_cmp_gt_i32 s9, -1
	v_or_b32_e32 v51, s9, v166
	v_cndmask_b32_e32 v229, v222, v65, vcc
	s_cselect_b64 s[10:11], -1, 0
	v_cmp_gt_i32_e32 vcc, s3, v51
	s_and_b64 vcc, s[10:11], vcc
	s_add_i32 s1, s0, 0x60
	v_cndmask_b32_e32 v230, v222, v34, vcc
	v_or_b32_e32 v34, s9, v184
	v_cmp_gt_i32_e32 vcc, s3, v34
	s_and_b64 vcc, s[10:11], vcc
	v_max3_f32 v66, v66, v70, v71
	v_cndmask_b32_e32 v231, v222, v35, vcc
	v_or_b32_e32 v35, s9, v185
	v_cmp_gt_i32_e32 vcc, s3, v35
	s_and_b64 vcc, s[10:11], vcc
	v_or_b32_e32 v35, s9, v186
	v_cndmask_b32_e32 v232, v222, v36, vcc
	v_cmp_gt_i32_e32 vcc, s3, v35
	s_and_b64 vcc, s[10:11], vcc
	v_or_b32_e32 v35, s9, v187
	v_cndmask_b32_e32 v233, v222, v37, vcc
	v_cmp_gt_i32_e32 vcc, s3, v35
	s_and_b64 vcc, s[10:11], vcc
	v_or_b32_e32 v35, s9, v188
	v_cndmask_b32_e32 v234, v222, v38, vcc
	v_cmp_gt_i32_e32 vcc, s3, v35
	s_and_b64 vcc, s[10:11], vcc
	v_or_b32_e32 v35, s9, v189
	v_cndmask_b32_e32 v235, v222, v39, vcc
	v_cmp_gt_i32_e32 vcc, s3, v35
	s_and_b64 vcc, s[10:11], vcc
	v_or_b32_e32 v35, s9, v190
	v_cndmask_b32_e32 v236, v222, v40, vcc
	v_cmp_gt_i32_e32 vcc, s3, v35
	s_and_b64 vcc, s[10:11], vcc
	v_or_b32_e32 v35, s9, v191
	v_cndmask_b32_e32 v237, v222, v41, vcc
	v_cmp_gt_i32_e32 vcc, s3, v35
	s_and_b64 vcc, s[10:11], vcc
	v_or_b32_e32 v35, s9, v192
	v_cndmask_b32_e32 v238, v222, v42, vcc
	v_cmp_gt_i32_e32 vcc, s3, v35
	s_and_b64 vcc, s[10:11], vcc
	v_or_b32_e32 v35, s9, v193
	v_cndmask_b32_e32 v239, v222, v43, vcc
	v_cmp_gt_i32_e32 vcc, s3, v35
	s_and_b64 vcc, s[10:11], vcc
	v_or_b32_e32 v35, s9, v194
	v_cndmask_b32_e32 v240, v222, v44, vcc
	v_cmp_gt_i32_e32 vcc, s3, v35
	s_and_b64 vcc, s[10:11], vcc
	v_or_b32_e32 v35, s9, v195
	v_cndmask_b32_e32 v241, v222, v45, vcc
	v_cmp_gt_i32_e32 vcc, s3, v35
	s_and_b64 vcc, s[10:11], vcc
	v_or_b32_e32 v35, s9, v196
	v_cndmask_b32_e32 v242, v222, v46, vcc
	v_cmp_gt_i32_e32 vcc, s3, v35
	s_and_b64 vcc, s[10:11], vcc
	v_or_b32_e32 v35, s9, v197
	v_cndmask_b32_e32 v243, v222, v47, vcc
	v_cmp_gt_i32_e32 vcc, s3, v35
	s_and_b64 vcc, s[10:11], vcc
	v_or_b32_e32 v35, s9, v198
	v_cndmask_b32_e32 v244, v222, v48, vcc
	v_cmp_gt_i32_e32 vcc, s3, v35
	s_and_b64 vcc, s[10:11], vcc
	s_cmpk_gt_i32 s0, 0xff9f
	v_or_b32_e32 v35, s1, v166
	v_cndmask_b32_e32 v245, v222, v49, vcc
	s_cselect_b64 s[10:11], -1, 0
; __device__ __forceinline__ void attn_phase_mfma(const Ctx& c, unsigned char* lds_raw, bool do_store) {
;     ...
;     #pragma unroll
;         for (int kb = 0; kb < 5; ++kb)
;     #pragma unroll
;             for (int e = 0; e < 16; ++e) {
;                 const int row = (e & 3) + 8 * (e >> 2) + 4 * h, rel = 32 * kb + row - rq, j = jbase + 32 * kb + row;
;                 const bool valid = (rel >= 0) && (rel <= 128) && (j >= 0) && (j < L);
;                 const float sv = valid ? sacc[kb][e] : -1e30f;
;                 sacc[kb][e] = sv; mx = fmaxf(mx, sv);
;             }
;         mx = fmaxf(mx, __shfl_xor(mx, 32));
	v_cmp_gt_i32_e32 vcc, s3, v35
	s_and_b64 vcc, s[10:11], vcc
	v_max3_f32 v66, v66, v72, v73
	v_cndmask_b32_e32 v246, v222, v18, vcc
	v_or_b32_e32 v18, s1, v184
	v_cmp_gt_i32_e32 vcc, s3, v18
	v_max3_f32 v66, v66, v74, v75
	s_and_b64 vcc, s[10:11], vcc
	v_max3_f32 v66, v66, v76, v77
	v_cndmask_b32_e32 v65, v222, v19, vcc
	v_or_b32_e32 v19, s1, v185
	v_max3_f32 v66, v66, v78, v79
	v_cmp_gt_i32_e32 vcc, s3, v19
	v_max3_f32 v66, v66, v80, v81
	s_and_b64 vcc, s[10:11], vcc
	v_or_b32_e32 v19, s1, v186
	v_max3_f32 v50, v66, v150, v151
	v_cndmask_b32_e32 v66, v222, v20, vcc
	v_cmp_gt_i32_e32 vcc, s3, v19
	s_and_b64 vcc, s[10:11], vcc
	v_or_b32_e32 v19, s1, v187
	v_cndmask_b32_e32 v63, v222, v21, vcc
	v_cmp_gt_i32_e32 vcc, s3, v19
	s_and_b64 vcc, s[10:11], vcc
	v_or_b32_e32 v19, s1, v188
	v_cndmask_b32_e32 v64, v222, v22, vcc
	v_cmp_gt_i32_e32 vcc, s3, v19
	s_and_b64 vcc, s[10:11], vcc
	v_or_b32_e32 v19, s1, v189
	v_cndmask_b32_e32 v61, v222, v23, vcc
	v_cmp_gt_i32_e32 vcc, s3, v19
	s_and_b64 vcc, s[10:11], vcc
	v_or_b32_e32 v19, s1, v190
	v_cndmask_b32_e32 v62, v222, v24, vcc
	v_cmp_gt_i32_e32 vcc, s3, v19
	s_and_b64 vcc, s[10:11], vcc
	v_or_b32_e32 v19, s1, v191
	v_cndmask_b32_e32 v59, v222, v25, vcc
	v_cmp_gt_i32_e32 vcc, s3, v19
	s_and_b64 vcc, s[10:11], vcc
	v_or_b32_e32 v19, s1, v192
	v_cndmask_b32_e32 v60, v222, v26, vcc
	v_cmp_gt_i32_e32 vcc, s3, v19
	s_and_b64 vcc, s[10:11], vcc
	v_or_b32_e32 v19, s1, v193
	v_cndmask_b32_e32 v57, v222, v27, vcc
	v_cmp_gt_i32_e32 vcc, s3, v19
	s_and_b64 vcc, s[10:11], vcc
	v_or_b32_e32 v19, s1, v194
	v_cndmask_b32_e32 v58, v222, v28, vcc
	v_cmp_gt_i32_e32 vcc, s3, v19
	s_and_b64 vcc, s[10:11], vcc
	v_or_b32_e32 v19, s1, v195
	v_cndmask_b32_e32 v55, v222, v29, vcc
	v_cmp_gt_i32_e32 vcc, s3, v19
	s_and_b64 vcc, s[10:11], vcc
	v_or_b32_e32 v19, s1, v196
	v_cndmask_b32_e32 v56, v222, v30, vcc
	v_cmp_gt_i32_e32 vcc, s3, v19
	s_and_b64 vcc, s[10:11], vcc
	v_or_b32_e32 v19, s1, v197
	v_cndmask_b32_e32 v53, v222, v31, vcc
	v_cmp_gt_i32_e32 vcc, s3, v19
	s_and_b64 vcc, s[10:11], vcc
	v_or_b32_e32 v19, s1, v198
	v_cndmask_b32_e32 v54, v222, v32, vcc
	v_cmp_gt_i32_e32 vcc, s3, v19
	s_and_b64 vcc, s[10:11], vcc
	s_add_i32 s9, s0, 0x80
	s_cmpk_gt_i32 s0, 0xff7f
	s_cselect_b64 s[0:1], -1, 0
	v_or_b32_e32 v19, s9, v166
	v_cndmask_b32_e32 v51, v222, v33, vcc
	s_and_b64 s[10:11], s[40:41], s[0:1]
	v_cmp_gt_i32_e32 vcc, s3, v19
	v_max3_f32 v50, v50, v152, v153
	s_and_b64 vcc, s[10:11], vcc
	v_max3_f32 v50, v50, v154, v155
	v_cndmask_b32_e32 v52, v222, v2, vcc
	v_or_b32_e32 v2, s9, v184
	v_max3_f32 v50, v50, v156, v157
	s_and_b64 s[10:11], s[42:43], s[0:1]
	v_cmp_gt_i32_e32 vcc, s3, v2
	v_max3_f32 v50, v50, v159, v169
	s_and_b64 vcc, s[10:11], vcc
	v_max3_f32 v50, v50, v224, v225
	v_cndmask_b32_e32 v49, v222, v3, vcc
	v_or_b32_e32 v3, s9, v185
	v_max3_f32 v50, v50, v226, v227
	s_and_b64 s[10:11], s[44:45], s[0:1]
	v_cmp_gt_i32_e32 vcc, s3, v3
	v_max3_f32 v50, v50, v228, v229
	s_and_b64 vcc, s[10:11], vcc
	v_or_b32_e32 v3, s9, v186
	v_max3_f32 v34, v50, v230, v231
	v_cndmask_b32_e32 v50, v222, v4, vcc
	s_and_b64 s[10:11], s[46:47], s[0:1]
	v_cmp_gt_i32_e32 vcc, s3, v3
	s_and_b64 vcc, s[10:11], vcc
	v_or_b32_e32 v3, s9, v187
	v_cndmask_b32_e32 v47, v222, v5, vcc
	s_and_b64 s[10:11], s[48:49], s[0:1]
	v_cmp_gt_i32_e32 vcc, s3, v3
	s_and_b64 vcc, s[10:11], vcc
	v_or_b32_e32 v3, s9, v188
	v_cndmask_b32_e32 v48, v222, v6, vcc
	s_and_b64 s[10:11], s[50:51], s[0:1]
	v_cmp_gt_i32_e32 vcc, s3, v3
	s_and_b64 vcc, s[10:11], vcc
	v_or_b32_e32 v3, s9, v189
	v_max3_f32 v34, v34, v232, v233
	v_cndmask_b32_e32 v45, v222, v7, vcc
	s_and_b64 s[10:11], s[52:53], s[0:1]
	v_cmp_gt_i32_e32 vcc, s3, v3
	v_max3_f32 v34, v34, v234, v235
	s_and_b64 vcc, s[10:11], vcc
	v_or_b32_e32 v3, s9, v190
	v_max3_f32 v34, v34, v236, v237
	v_cndmask_b32_e32 v46, v222, v8, vcc
	s_and_b64 s[10:11], s[54:55], s[0:1]
	v_cmp_gt_i32_e32 vcc, s3, v3
	v_max3_f32 v34, v34, v238, v239
	s_and_b64 vcc, s[10:11], vcc
	v_or_b32_e32 v3, s9, v191
	v_max3_f32 v34, v34, v240, v241
	v_cndmask_b32_e32 v43, v222, v9, vcc
	s_and_b64 s[10:11], s[56:57], s[0:1]
	v_cmp_gt_i32_e32 vcc, s3, v3
	v_max3_f32 v34, v34, v242, v243
	s_and_b64 vcc, s[10:11], vcc
	v_or_b32_e32 v3, s9, v192
	v_max3_f32 v34, v34, v244, v245
	v_cndmask_b32_e32 v44, v222, v10, vcc
	s_and_b64 s[10:11], s[58:59], s[0:1]
	v_cmp_gt_i32_e32 vcc, s3, v3
	v_max3_f32 v18, v34, v246, v65
	s_and_b64 vcc, s[10:11], vcc
	v_or_b32_e32 v3, s9, v193
	v_max3_f32 v18, v18, v66, v63
	v_cndmask_b32_e32 v41, v222, v11, vcc
	s_and_b64 s[10:11], s[60:61], s[0:1]
	v_cmp_gt_i32_e32 vcc, s3, v3
	v_max3_f32 v18, v18, v64, v61
	s_and_b64 vcc, s[10:11], vcc
	v_or_b32_e32 v3, s9, v194
	v_max3_f32 v18, v18, v62, v59
	v_cndmask_b32_e32 v42, v222, v12, vcc
	s_and_b64 s[10:11], s[62:63], s[0:1]
	v_cmp_gt_i32_e32 vcc, s3, v3
	v_max3_f32 v18, v18, v60, v57
	s_and_b64 vcc, s[10:11], vcc
	v_or_b32_e32 v3, s9, v195
	v_max3_f32 v18, v18, v58, v55
	v_cndmask_b32_e32 v39, v222, v13, vcc
	s_and_b64 s[10:11], s[64:65], s[0:1]
	v_cmp_gt_i32_e32 vcc, s3, v3
	v_max3_f32 v18, v18, v56, v53
	s_and_b64 vcc, s[10:11], vcc
	v_or_b32_e32 v3, s9, v196
	v_max3_f32 v18, v18, v54, v51
	v_cndmask_b32_e32 v40, v222, v14, vcc
	s_and_b64 s[10:11], s[66:67], s[0:1]
	v_cmp_gt_i32_e32 vcc, s3, v3
	v_max3_f32 v2, v18, v52, v49
	s_and_b64 vcc, s[10:11], vcc
	v_or_b32_e32 v3, s9, v197
	v_max3_f32 v2, v2, v50, v47
	v_cndmask_b32_e32 v36, v222, v15, vcc
	s_and_b64 s[10:11], s[68:69], s[0:1]
	v_cmp_gt_i32_e32 vcc, s3, v3
	v_max3_f32 v2, v2, v48, v45
	s_and_b64 vcc, s[10:11], vcc
	v_or_b32_e32 v3, s9, v198
	v_max3_f32 v2, v2, v46, v43
	v_cndmask_b32_e32 v37, v222, v16, vcc
	s_and_b64 s[0:1], s[70:71], s[0:1]
	v_cmp_gt_i32_e32 vcc, s3, v3
	v_and_b32_e32 v4, 64, v220
	v_max3_f32 v2, v2, v44, v41
	s_and_b64 vcc, s[0:1], vcc
	v_xor_b32_e32 v3, 32, v220
	v_add_u32_e32 v4, 64, v4
	v_max3_f32 v2, v2, v42, v39
	v_cndmask_b32_e32 v38, v222, v17, vcc
	v_cmp_lt_i32_e32 vcc, v3, v4
	v_max3_f32 v2, v2, v40, v36
	v_max3_f32 v2, v2, v37, v38
	v_cndmask_b32_e32 v3, v220, v3, vcc
	v_lshlrev_b32_e32 v35, 2, v3
	ds_bpermute_b32 v3, v35, v2
	s_waitcnt lgkmcnt(0)
; #define LASP __attribute__((address_space(3)))
; __device__ __forceinline__ unsigned cvtpk(float lo, float hi) { return pk2(lo, hi); }
; __device__ __forceinline__ void attn_phase_mfma(const Ctx& c, unsigned char* lds_raw, bool do_store) {
;     ...
;         float lsum = 0.f;
;     #pragma unroll
;         for (int kb = 0; kb < 5; ++kb)
;     #pragma unroll
;             for (int e = 0; e < 16; ++e) { const float p = __builtin_amdgcn_exp2f(sacc[kb][e] - mx); sacc[kb][e] = p; lsum += p; }
;         lsum += __shfl_xor(lsum, 32);
;         f32x16 oacc[2];
;     #pragma unroll
;         for (int db = 0; db < 2; ++db)
;     #pragma unroll
;             for (int e = 0; e < 16; ++e) oacc[db][e] = 0.f;
;     #pragma unroll
;         for (int kb = 0; kb < 5; ++kb)
;     #pragma unroll
;             for (int s2 = 0; s2 < 2; ++s2) {
;                 u32x4 pw;
;     #pragma unroll
;                 for (int e = 0; e < 4; ++e) pw[e] = cvtpk(sacc[kb][8 * s2 + 2 * e], sacc[kb][8 * s2 + 2 * e + 1]);
;                 const bf16x8 pf = __builtin_bit_cast(bf16x8, pw);
;                 const int kp = (32 * wave + 32 * kb + 16 * s2 + 4 * h) >> 1;
;     #pragma unroll
;                 for (int db = 0; db < 2; ++db) {
;                     const LASP unsigned* vp = Vt + (32 * db + rq) * 194 + kp;
;                     const u32x2 g0 = *(const LASP u32x2*)vp, g1 = *(const LASP u32x2*)(vp + 4);
;                     const u32x4 aw = (u32x4){g0.x, g0.y, g1.x, g1.y};
;                     oacc[db] = mfma32_g(__builtin_bit_cast(bf16x8, aw), pf, oacc[db]);
;                 }
;             }
	v_max_f32_e32 v3, v3, v3
	v_max_f32_e32 v34, v2, v3
	v_sub_f32_e32 v2, v107, v34
	v_exp_f32_e32 v6, v2
	v_sub_f32_e32 v2, v67, v34
	v_exp_f32_e32 v7, v2
	v_sub_f32_e32 v2, v68, v34
	v_exp_f32_e32 v8, v2
	v_sub_f32_e32 v3, v69, v34
	v_exp_f32_e32 v9, v3
	v_sub_f32_e32 v3, v70, v34
	v_add_f32_e32 v2, 0, v6
	v_exp_f32_e32 v10, v3
	v_sub_f32_e32 v3, v71, v34
	v_add_f32_e32 v2, v7, v2
	v_exp_f32_e32 v11, v3
	v_sub_f32_e32 v3, v72, v34
	v_add_f32_e32 v2, v8, v2
	v_exp_f32_e32 v12, v3
	v_sub_f32_e32 v3, v73, v34
	v_add_f32_e32 v2, v9, v2
	v_exp_f32_e32 v13, v3
	v_sub_f32_e32 v3, v74, v34
	v_add_f32_e32 v2, v10, v2
	v_exp_f32_e32 v67, v3
	v_sub_f32_e32 v3, v75, v34
	v_add_f32_e32 v2, v11, v2
	v_exp_f32_e32 v107, v3
	v_sub_f32_e32 v3, v76, v34
	v_add_f32_e32 v2, v12, v2
	v_exp_f32_e32 v76, v3
	v_sub_f32_e32 v3, v77, v34
	v_add_f32_e32 v2, v13, v2
	v_exp_f32_e32 v77, v3
	v_sub_f32_e32 v3, v78, v34
	v_add_f32_e32 v2, v67, v2
	v_exp_f32_e32 v78, v3
	v_sub_f32_e32 v3, v79, v34
	v_add_f32_e32 v2, v107, v2
	v_exp_f32_e32 v79, v3
	v_sub_f32_e32 v3, v80, v34
	v_add_f32_e32 v2, v76, v2
	v_exp_f32_e32 v80, v3
	v_sub_f32_e32 v3, v81, v34
	v_add_f32_e32 v2, v77, v2
	v_exp_f32_e32 v81, v3
	v_sub_f32_e32 v3, v150, v34
	v_add_f32_e32 v2, v78, v2
	v_exp_f32_e32 v150, v3
	v_sub_f32_e32 v3, v151, v34
	v_add_f32_e32 v2, v79, v2
	v_exp_f32_e32 v151, v3
	v_sub_f32_e32 v3, v152, v34
	v_add_f32_e32 v2, v80, v2
	v_exp_f32_e32 v152, v3
	v_sub_f32_e32 v3, v153, v34
	v_add_f32_e32 v2, v81, v2
	v_exp_f32_e32 v153, v3
	v_sub_f32_e32 v3, v154, v34
	v_add_f32_e32 v2, v150, v2
	v_exp_f32_e32 v154, v3
	v_sub_f32_e32 v3, v155, v34
	v_add_f32_e32 v2, v151, v2
	v_exp_f32_e32 v155, v3
	v_sub_f32_e32 v3, v156, v34
	v_add_f32_e32 v2, v152, v2
	v_exp_f32_e32 v156, v3
	v_sub_f32_e32 v3, v157, v34
	v_add_f32_e32 v2, v153, v2
	v_exp_f32_e32 v157, v3
	v_sub_f32_e32 v3, v159, v34
	v_add_f32_e32 v2, v154, v2
	v_exp_f32_e32 v159, v3
	v_sub_f32_e32 v3, v169, v34
	v_add_f32_e32 v2, v155, v2
	v_exp_f32_e32 v169, v3
	v_sub_f32_e32 v3, v224, v34
	v_add_f32_e32 v2, v156, v2
	v_exp_f32_e32 v224, v3
	v_sub_f32_e32 v3, v225, v34
	v_add_f32_e32 v2, v157, v2
	v_exp_f32_e32 v225, v3
	v_sub_f32_e32 v3, v226, v34
	v_add_f32_e32 v2, v159, v2
	v_exp_f32_e32 v226, v3
	v_sub_f32_e32 v3, v227, v34
	v_add_f32_e32 v2, v169, v2
	v_exp_f32_e32 v227, v3
	v_sub_f32_e32 v3, v228, v34
	v_add_f32_e32 v2, v224, v2
	v_exp_f32_e32 v228, v3
	v_sub_f32_e32 v3, v229, v34
	v_add_f32_e32 v2, v225, v2
	v_exp_f32_e32 v229, v3
	v_sub_f32_e32 v3, v230, v34
	v_add_f32_e32 v2, v226, v2
	v_exp_f32_e32 v230, v3
	v_sub_f32_e32 v3, v231, v34
	v_add_f32_e32 v2, v227, v2
	v_exp_f32_e32 v231, v3
	v_sub_f32_e32 v3, v232, v34
	v_add_f32_e32 v2, v228, v2
	v_exp_f32_e32 v232, v3
	v_sub_f32_e32 v3, v233, v34
	v_add_f32_e32 v2, v229, v2
	v_exp_f32_e32 v233, v3
	v_sub_f32_e32 v3, v234, v34
	v_add_f32_e32 v2, v230, v2
	v_exp_f32_e32 v234, v3
	v_sub_f32_e32 v3, v235, v34
	v_add_f32_e32 v2, v231, v2
	v_exp_f32_e32 v235, v3
	v_sub_f32_e32 v3, v236, v34
	v_add_f32_e32 v2, v232, v2
	v_exp_f32_e32 v236, v3
	v_sub_f32_e32 v3, v237, v34
	v_add_f32_e32 v2, v233, v2
	v_exp_f32_e32 v237, v3
	v_sub_f32_e32 v3, v238, v34
	v_add_f32_e32 v2, v234, v2
	v_exp_f32_e32 v238, v3
	v_sub_f32_e32 v3, v239, v34
	v_add_f32_e32 v2, v235, v2
	v_exp_f32_e32 v239, v3
	v_sub_f32_e32 v3, v240, v34
	v_add_f32_e32 v2, v236, v2
	v_exp_f32_e32 v240, v3
	v_add_f32_e32 v2, v237, v2
	v_add_f32_e32 v2, v238, v2
	v_add_f32_e32 v2, v239, v2
	v_add_f32_e32 v14, v240, v2
	v_add_u32_e32 v2, v200, v199
	v_add_u32_e32 v247, 0xc000, v2
	ds_read2_b64 v[2:5], v247 offset1:2
	v_cvt_pk_bf16_f32 v68, v6, v7
	v_cvt_pk_bf16_f32 v69, v8, v9
	v_cvt_pk_bf16_f32 v70, v10, v11
	v_cvt_pk_bf16_f32 v71, v12, v13
	v_sub_f32_e32 v15, v241, v34
	v_exp_f32_e32 v241, v15
	s_waitcnt lgkmcnt(0)
	v_mfma_f32_32x32x16_bf16 v[18:33], v[2:5], v[68:71], 0
	v_add_u32_e32 v2, v200, v201
	v_add_u32_e32 v248, 0xc000, v2
	ds_read2_b64 v[72:75], v248 offset1:2
	v_sub_f32_e32 v15, v242, v34
	v_exp_f32_e32 v242, v15
	v_sub_f32_e32 v2, v243, v34
	v_exp_f32_e32 v243, v2
	v_sub_f32_e32 v2, v244, v34
	v_exp_f32_e32 v244, v2
	v_add_f32_e32 v2, v241, v14
	v_add_f32_e32 v2, v242, v2
	v_add_f32_e32 v2, v243, v2
	v_add_f32_e32 v249, v244, v2
	s_waitcnt lgkmcnt(0)
	v_mfma_f32_32x32x16_bf16 v[2:17], v[72:75], v[68:71], 0
	ds_read2_b64 v[68:71], v247 offset0:4 offset1:6
	v_sub_f32_e32 v72, v245, v34
	v_exp_f32_e32 v245, v72
	v_sub_f32_e32 v72, v246, v34
	v_exp_f32_e32 v246, v72
	v_cvt_pk_bf16_f32 v72, v67, v107
	v_cvt_pk_bf16_f32 v73, v76, v77
	v_cvt_pk_bf16_f32 v74, v78, v79
	v_cvt_pk_bf16_f32 v75, v80, v81
	v_sub_f32_e32 v65, v65, v34
	v_exp_f32_e32 v76, v65
	s_waitcnt lgkmcnt(0)
	v_mfma_f32_32x32x16_bf16 v[18:33], v[68:71], v[72:75], v[18:33]
	ds_read2_b64 v[68:71], v248 offset0:4 offset1:6
	v_sub_f32_e32 v65, v66, v34
	v_exp_f32_e32 v77, v65
	v_add_f32_e32 v65, v245, v249
	v_add_f32_e32 v65, v246, v65
	v_add_f32_e32 v65, v76, v65
	v_add_f32_e32 v78, v77, v65
	v_add_u32_e32 v65, v202, v199
	v_add_u32_e32 v65, 0xc000, v65
	s_waitcnt lgkmcnt(0)
	v_mfma_f32_32x32x16_bf16 v[2:17], v[68:71], v[72:75], v[2:17]
	ds_read2_b64 v[66:69], v65 offset1:2
	v_sub_f32_e32 v63, v63, v34
	v_exp_f32_e32 v74, v63
	v_sub_f32_e32 v63, v64, v34
	v_exp_f32_e32 v75, v63
	v_add_u32_e32 v63, v202, v201
	v_cvt_pk_bf16_f32 v70, v150, v151
	v_cvt_pk_bf16_f32 v71, v152, v153
	v_cvt_pk_bf16_f32 v72, v154, v155
	v_cvt_pk_bf16_f32 v73, v156, v157
	v_add_u32_e32 v63, 0xc000, v63
	v_sub_f32_e32 v61, v61, v34
	s_waitcnt lgkmcnt(0)
; #define LASP __attribute__((address_space(3)))
; __device__ __forceinline__ unsigned cvtpk(float lo, float hi) { return pk2(lo, hi); }
; __device__ __forceinline__ void attn_phase_mfma(const Ctx& c, unsigned char* lds_raw, bool do_store) {
;     ...
;     #pragma unroll
;         for (int kb = 0; kb < 5; ++kb)
;     #pragma unroll
;             for (int s2 = 0; s2 < 2; ++s2) {
;                 u32x4 pw;
;     #pragma unroll
;                 for (int e = 0; e < 4; ++e) pw[e] = cvtpk(sacc[kb][8 * s2 + 2 * e], sacc[kb][8 * s2 + 2 * e + 1]);
;                 const bf16x8 pf = __builtin_bit_cast(bf16x8, pw);
;                 const int kp = (32 * wave + 32 * kb + 16 * s2 + 4 * h) >> 1;
;     #pragma unroll
;                 for (int db = 0; db < 2; ++db) {
;                     const LASP unsigned* vp = Vt + (32 * db + rq) * 194 + kp;
;                     const u32x2 g0 = *(const LASP u32x2*)vp, g1 = *(const LASP u32x2*)(vp + 4);
;                     const u32x4 aw = (u32x4){g0.x, g0.y, g1.x, g1.y};
;                     oacc[db] = mfma32_g(__builtin_bit_cast(bf16x8, aw), pf, oacc[db]);
;                 }
;             }
	v_mfma_f32_32x32x16_bf16 v[18:33], v[66:69], v[70:73], v[18:33]
	ds_read2_b64 v[64:67], v63 offset1:2
	v_exp_f32_e32 v79, v61
	v_sub_f32_e32 v61, v62, v34
	v_exp_f32_e32 v80, v61
	v_add_f32_e32 v61, v74, v78
	v_add_f32_e32 v61, v75, v61
	v_add_f32_e32 v61, v79, v61
	v_add_f32_e32 v78, v80, v61
	v_add_u32_e32 v61, v203, v199
	v_add_u32_e32 v61, 0xc000, v61
	s_waitcnt lgkmcnt(0)
	v_mfma_f32_32x32x16_bf16 v[2:17], v[64:67], v[70:73], v[2:17]
	ds_read2_b64 v[62:65], v61 offset1:2
	v_sub_f32_e32 v59, v59, v34
	v_exp_f32_e32 v70, v59
	v_sub_f32_e32 v59, v60, v34
	v_exp_f32_e32 v71, v59
	v_add_u32_e32 v59, v203, v201
	v_cvt_pk_bf16_f32 v66, v159, v169
	v_cvt_pk_bf16_f32 v67, v224, v225
	v_cvt_pk_bf16_f32 v68, v226, v227
	v_cvt_pk_bf16_f32 v69, v228, v229
	v_add_u32_e32 v59, 0xc000, v59
	v_sub_f32_e32 v57, v57, v34
	s_waitcnt lgkmcnt(0)
	v_mfma_f32_32x32x16_bf16 v[18:33], v[62:65], v[66:69], v[18:33]
	ds_read2_b64 v[60:63], v59 offset1:2
	v_exp_f32_e32 v72, v57
	v_sub_f32_e32 v57, v58, v34
	v_exp_f32_e32 v73, v57
	v_add_f32_e32 v57, v70, v78
	v_add_f32_e32 v57, v71, v57
	v_add_f32_e32 v57, v72, v57
	v_add_f32_e32 v78, v73, v57
	v_add_u32_e32 v57, v204, v199
	v_add_u32_e32 v57, 0xc000, v57
	s_waitcnt lgkmcnt(0)
	v_mfma_f32_32x32x16_bf16 v[2:17], v[60:63], v[66:69], v[2:17]
	ds_read2_b64 v[58:61], v57 offset1:2
	v_sub_f32_e32 v55, v55, v34
	v_exp_f32_e32 v66, v55
	v_sub_f32_e32 v55, v56, v34
	v_exp_f32_e32 v67, v55
	v_add_u32_e32 v55, v204, v201
	v_cvt_pk_bf16_f32 v62, v230, v231
	v_cvt_pk_bf16_f32 v63, v232, v233
	v_cvt_pk_bf16_f32 v64, v234, v235
	v_cvt_pk_bf16_f32 v65, v236, v237
	v_add_u32_e32 v55, 0xc000, v55
	v_sub_f32_e32 v53, v53, v34
	s_waitcnt lgkmcnt(0)
	v_mfma_f32_32x32x16_bf16 v[18:33], v[58:61], v[62:65], v[18:33]
	ds_read2_b64 v[56:59], v55 offset1:2
	v_exp_f32_e32 v68, v53
	v_sub_f32_e32 v53, v54, v34
	v_exp_f32_e32 v69, v53
	v_add_f32_e32 v53, v66, v78
	v_add_f32_e32 v53, v67, v53
	v_add_f32_e32 v53, v68, v53
	v_add_f32_e32 v78, v69, v53
	v_add_u32_e32 v53, v205, v199
	v_add_u32_e32 v53, 0xc000, v53
	s_waitcnt lgkmcnt(0)
	v_mfma_f32_32x32x16_bf16 v[2:17], v[56:59], v[62:65], v[2:17]
	ds_read2_b64 v[54:57], v53 offset1:2
	v_sub_f32_e32 v51, v51, v34
	v_exp_f32_e32 v62, v51
	v_sub_f32_e32 v51, v52, v34
	v_exp_f32_e32 v63, v51
	v_add_u32_e32 v51, v205, v201
	v_cvt_pk_bf16_f32 v58, v238, v239
	v_cvt_pk_bf16_f32 v59, v240, v241
	v_cvt_pk_bf16_f32 v60, v242, v243
	v_cvt_pk_bf16_f32 v61, v244, v245
	v_add_u32_e32 v51, 0xc000, v51
	v_sub_f32_e32 v49, v49, v34
	s_waitcnt lgkmcnt(0)
	v_mfma_f32_32x32x16_bf16 v[18:33], v[54:57], v[58:61], v[18:33]
	ds_read2_b64 v[52:55], v51 offset1:2
	v_exp_f32_e32 v64, v49
	v_sub_f32_e32 v49, v50, v34
	v_exp_f32_e32 v65, v49
	v_add_f32_e32 v49, v62, v78
	v_add_f32_e32 v49, v63, v49
	v_add_f32_e32 v49, v64, v49
	v_add_f32_e32 v78, v65, v49
	v_add_u32_e32 v49, v206, v199
	v_add_u32_e32 v49, 0xc000, v49
	s_waitcnt lgkmcnt(0)
	v_mfma_f32_32x32x16_bf16 v[2:17], v[52:55], v[58:61], v[2:17]
	ds_read2_b64 v[50:53], v49 offset1:2
	v_sub_f32_e32 v47, v47, v34
	v_exp_f32_e32 v58, v47
	v_sub_f32_e32 v47, v48, v34
	v_exp_f32_e32 v59, v47
	v_add_u32_e32 v47, v206, v201
	v_cvt_pk_bf16_f32 v54, v246, v76
	v_cvt_pk_bf16_f32 v55, v77, v74
	v_cvt_pk_bf16_f32 v56, v75, v79
	v_cvt_pk_bf16_f32 v57, v80, v70
	v_add_u32_e32 v47, 0xc000, v47
	v_sub_f32_e32 v45, v45, v34
	s_waitcnt lgkmcnt(0)
	v_mfma_f32_32x32x16_bf16 v[18:33], v[50:53], v[54:57], v[18:33]
	ds_read2_b64 v[48:51], v47 offset1:2
	v_exp_f32_e32 v60, v45
	v_sub_f32_e32 v45, v46, v34
	v_exp_f32_e32 v61, v45
	v_add_f32_e32 v45, v58, v78
	v_add_f32_e32 v45, v59, v45
	v_add_f32_e32 v45, v60, v45
	v_add_f32_e32 v70, v61, v45
	v_add_u32_e32 v45, v207, v199
	v_add_u32_e32 v45, 0xc000, v45
	s_waitcnt lgkmcnt(0)
	v_mfma_f32_32x32x16_bf16 v[2:17], v[48:51], v[54:57], v[2:17]
	ds_read2_b64 v[46:49], v45 offset1:2
	v_sub_f32_e32 v43, v43, v34
	v_exp_f32_e32 v54, v43
	v_sub_f32_e32 v43, v44, v34
	v_exp_f32_e32 v55, v43
	v_add_u32_e32 v43, v207, v201
	v_cvt_pk_bf16_f32 v50, v71, v72
	v_cvt_pk_bf16_f32 v51, v73, v66
	v_cvt_pk_bf16_f32 v52, v67, v68
	v_cvt_pk_bf16_f32 v53, v69, v62
	v_add_u32_e32 v43, 0xc000, v43
	v_sub_f32_e32 v41, v41, v34
	s_waitcnt lgkmcnt(0)
	v_mfma_f32_32x32x16_bf16 v[18:33], v[46:49], v[50:53], v[18:33]
	ds_read2_b64 v[44:47], v43 offset1:2
	v_exp_f32_e32 v56, v41
	v_sub_f32_e32 v41, v42, v34
	v_exp_f32_e32 v57, v41
	v_add_f32_e32 v41, v54, v70
	v_add_f32_e32 v41, v55, v41
	v_add_f32_e32 v41, v56, v41
	v_add_f32_e32 v62, v57, v41
	v_add_u32_e32 v41, v208, v199
	v_add_u32_e32 v41, 0xc000, v41
	s_waitcnt lgkmcnt(0)
; __device__ __forceinline__ unsigned cvtpk(float lo, float hi) { return pk2(lo, hi); }
; __device__ __forceinline__ void attn_phase_mfma(const Ctx& c, unsigned char* lds_raw, bool do_store) {
;     ...
;         if (do_store) {
;             const float inv = 1.f / lsum;
;     #pragma unroll
;             for (int db = 0; db < 2; ++db)
;     #pragma unroll
;                 for (int g4 = 0; g4 < 4; ++g4) {
;                     const u32x2 w = (u32x2){cvtpk(oacc[db][4 * g4] * inv, oacc[db][4 * g4 + 1] * inv), cvtpk(oacc[db][4 * g4 + 2] * inv, oacc[db][4 * g4 + 3] * inv)};
;                     *(u32x2*)(qrow + 32 * db + 8 * g4 + 4 * h) = w;
;                 }
	v_mfma_f32_32x32x16_bf16 v[2:17], v[44:47], v[50:53], v[2:17]
	ds_read2_b64 v[42:45], v41 offset1:2
	v_sub_f32_e32 v39, v39, v34
	v_exp_f32_e32 v50, v39
	v_sub_f32_e32 v39, v40, v34
	v_exp_f32_e32 v51, v39
	v_add_u32_e32 v39, v208, v201
	v_cvt_pk_bf16_f32 v46, v63, v64
	v_cvt_pk_bf16_f32 v47, v65, v58
	v_cvt_pk_bf16_f32 v48, v59, v60
	v_cvt_pk_bf16_f32 v49, v61, v54
	v_add_u32_e32 v39, 0xc000, v39
	v_sub_f32_e32 v36, v36, v34
	s_waitcnt lgkmcnt(0)
	v_mfma_f32_32x32x16_bf16 v[18:33], v[42:45], v[46:49], v[18:33]
	ds_read2_b64 v[40:43], v39 offset1:2
	v_exp_f32_e32 v45, v36
	v_sub_f32_e32 v36, v37, v34
	v_exp_f32_e32 v52, v36
	v_sub_f32_e32 v36, v38, v34
	v_exp_f32_e32 v53, v36
	v_add_u32_e32 v36, v209, v199
	v_add_f32_e32 v39, v50, v62
	v_add_u32_e32 v36, 0xc000, v36
	v_add_f32_e32 v44, v51, v39
	s_waitcnt lgkmcnt(0)
	v_mfma_f32_32x32x16_bf16 v[2:17], v[40:43], v[46:49], v[2:17]
	ds_read2_b64 v[36:39], v36 offset1:2
	v_add_f32_e32 v40, v45, v44
	v_add_f32_e32 v40, v52, v40
	v_add_f32_e32 v44, v53, v40
	v_cvt_pk_bf16_f32 v40, v55, v56
	v_cvt_pk_bf16_f32 v41, v57, v50
	v_cvt_pk_bf16_f32 v42, v51, v45
	v_cvt_pk_bf16_f32 v43, v52, v53
	ds_bpermute_b32 v35, v35, v44
	s_waitcnt lgkmcnt(0)
	v_add_f32_e32 v35, v44, v35
	v_mfma_f32_32x32x16_bf16 v[18:33], v[36:39], v[40:43], v[18:33]
	v_add_u32_e32 v36, v209, v201
	v_add_u32_e32 v36, 0xc000, v36
	ds_read2_b64 v[36:39], v36 offset1:2
	v_div_scale_f32 v44, s[0:1], v35, v35, 1.0
	v_rcp_f32_e32 v45, v44
	s_waitcnt lgkmcnt(0)
	v_mfma_f32_32x32x16_bf16 v[2:17], v[36:39], v[40:43], v[2:17]
	v_fma_f32 v36, -v44, v45, 1.0
	v_fmac_f32_e32 v45, v36, v45
	v_div_scale_f32 v36, vcc, 1.0, v35, 1.0
	v_mul_f32_e32 v37, v36, v45
	v_fma_f32 v38, -v44, v37, v36
	v_fmac_f32_e32 v37, v38, v45
	v_fma_f32 v36, -v44, v37, v36
	v_div_fmas_f32 v36, v36, v45, v37
	s_nop 15
	s_nop 15
	v_div_fixup_f32 v36, v36, v35, 1.0
	v_lshlrev_b32_e32 v38, 1, v166
	v_and_b32_e32 v39, 32, v0
	v_lshrrev_b32_e32 v39, 2, v39
	v_add_u32_e32 v38, v38, v39
	v_mov_b32_e32 v39, v106
	v_lshl_add_u64 v[38:39], v[174:175], 0, v[38:39]
	v_pk_mul_f32 v[18:19], v[18:19], v[36:37] op_sel_hi:[1,0]
	v_pk_mul_f32 v[20:21], v[20:21], v[36:37] op_sel_hi:[1,0]
	v_cvt_pk_bf16_f32 v18, v18, v19
	v_cvt_pk_bf16_f32 v19, v20, v21
	v_pk_mul_f32 v[20:21], v[22:23], v[36:37] op_sel_hi:[1,0]
	v_pk_mul_f32 v[22:23], v[24:25], v[36:37] op_sel_hi:[1,0]
	v_cvt_pk_bf16_f32 v20, v20, v21
	v_cvt_pk_bf16_f32 v21, v22, v23
	v_pk_mul_f32 v[2:3], v[2:3], v[36:37] op_sel_hi:[1,0]
	v_pk_mul_f32 v[4:5], v[4:5], v[36:37] op_sel_hi:[1,0]
	v_permlane32_swap_b32_e32 v18, v20
	v_permlane32_swap_b32_e32 v19, v21
	v_cvt_pk_bf16_f32 v2, v2, v3
	v_cvt_pk_bf16_f32 v3, v4, v5
	v_pk_mul_f32 v[4:5], v[6:7], v[36:37] op_sel_hi:[1,0]
	v_pk_mul_f32 v[6:7], v[8:9], v[36:37] op_sel_hi:[1,0]
	global_store_dwordx4 v[38:39], v[18:21], off offset:1536
	v_cvt_pk_bf16_f32 v4, v4, v5
	v_cvt_pk_bf16_f32 v5, v6, v7
	v_pk_mul_f32 v[22:23], v[26:27], v[36:37] op_sel_hi:[1,0]
	v_pk_mul_f32 v[24:25], v[28:29], v[36:37] op_sel_hi:[1,0]
	v_permlane32_swap_b32_e32 v2, v4
	v_permlane32_swap_b32_e32 v3, v5
	v_cvt_pk_bf16_f32 v22, v22, v23
	v_cvt_pk_bf16_f32 v23, v24, v25
	v_pk_mul_f32 v[24:25], v[30:31], v[36:37] op_sel_hi:[1,0]
	v_pk_mul_f32 v[26:27], v[32:33], v[36:37] op_sel_hi:[1,0]
	global_store_dwordx4 v[38:39], v[2:5], off offset:1600
	v_cvt_pk_bf16_f32 v24, v24, v25
	v_cvt_pk_bf16_f32 v25, v26, v27
	v_pk_mul_f32 v[6:7], v[10:11], v[36:37] op_sel_hi:[1,0]
	v_pk_mul_f32 v[8:9], v[12:13], v[36:37] op_sel_hi:[1,0]
	v_permlane32_swap_b32_e32 v22, v24
	v_permlane32_swap_b32_e32 v23, v25
	v_cvt_pk_bf16_f32 v6, v6, v7
	v_cvt_pk_bf16_f32 v7, v8, v9
	v_pk_mul_f32 v[8:9], v[14:15], v[36:37] op_sel_hi:[1,0]
	v_pk_mul_f32 v[10:11], v[16:17], v[36:37] op_sel_hi:[1,0]
	global_store_dwordx4 v[38:39], v[22:25], off offset:1568
	v_cvt_pk_bf16_f32 v8, v8, v9
	v_cvt_pk_bf16_f32 v9, v10, v11
	s_nop 1
	v_permlane32_swap_b32_e32 v6, v8
	v_permlane32_swap_b32_e32 v7, v9
	global_store_dwordx4 v[38:39], v[6:9], off offset:1632
	s_mov_b64 s[0:1], exec
	v_readlane_b32 s10, v255, 15
	v_readlane_b32 s11, v255, 16
	s_and_b64 s[10:11], s[0:1], s[10:11]
	s_mov_b64 exec, s[10:11]
	s_cbranch_execz .LBB0_358
	s_mov_b32 s3, 0x800000
	v_cmp_gt_f32_e32 vcc, s3, v35
	s_mov_b32 s3, 0x3f317217
	s_ashr_i32 s89, s88, 31
	v_cndmask_b32_e64 v2, 0, 32, vcc
	v_ldexp_f32 v2, v35, v2
	v_log_f32_e32 v2, v2
	v_cndmask_b32_e32 v3, 0, v223, vcc
	s_lshl_b64 s[10:11], s[88:89], 19
	v_mul_f32_e32 v4, 0x3f317217, v2
	v_fma_f32 v4, v2, s3, -v4
	s_mov_b32 s3, 0x7f800000
	v_fmac_f32_e32 v4, 0x3377d1cf, v2
	v_cmp_lt_f32_e64 vcc, |v2|, s3
	v_readlane_b32 s3, v255, 13
	v_fmac_f32_e32 v4, 0x3f317217, v2
	s_add_u32 s10, s3, s10
	v_readlane_b32 s3, v255, 14
	v_cndmask_b32_e32 v2, v2, v4, vcc
	s_addc_u32 s11, s3, s11
	v_sub_f32_e32 v4, v2, v3
	v_lshl_add_u64 v[2:3], v[108:109], 4, s[10:11]
	s_lshl_b32 s96, s2, 2
	v_fmac_f32_e32 v4, 0x3f317218, v34
	v_lshl_add_u64 v[2:3], v[2:3], 0, s[96:97]
	global_store_dword v[2:3], v4, off
	s_branch .LBB0_358

; __device__ __forceinline__ float bflo(unsigned w) { return __uint_as_float(w << 16); }
; __device__ __forceinline__ float bfhi(unsigned w) { return __uint_as_float(w & 0xffff0000u); }
; __device__ __forceinline__ unsigned pk2(float lo, float hi) { const f32x2n v = {lo, hi}; return __builtin_bit_cast(unsigned, __builtin_convertvector(v, bf16x2n)); }
; __device__ __forceinline__ void attn_phase_mfma(const Ctx& c, unsigned char* lds_raw, bool do_store) {
;     ...
;         {
;             const u32x4 q0 = qn[0], q1 = qn[1], q2 = qn[2], q3 = qn[3];
;             const h16x8 cav = tq[0], cbv = tq[1], sav = tq[2], sbv = tq[3];
;             const float sc = 0.125f * 1.44269504f;
;             u32x4 o0, o1, o2, o3;
;     #pragma unroll
;             for (int e = 0; e < 4; ++e) {
;                 const float ca_0 = (float)cav[2 * e], ca_1 = (float)cav[2 * e + 1], sa_0 = (float)sav[2 * e], sa_1 = (float)sav[2 * e + 1];
;                 const float cb_0 = (float)cbv[2 * e], cb_1 = (float)cbv[2 * e + 1], sb_0 = (float)sbv[2 * e], sb_1 = (float)sbv[2 * e + 1];
;                 const float a0 = bflo(q0[e]), a1 = bfhi(q0[e]), b0 = bflo(q2[e]), b1 = bfhi(q2[e]);
;                 const float e0 = bflo(q1[e]), e1 = bfhi(q1[e]), f0 = bflo(q3[e]), f1 = bfhi(q3[e]);
;                 o0[e] = pk2((a0 * ca_0 - b0 * sa_0) * sc, (a1 * ca_1 - b1 * sa_1) * sc);
;                 o2[e] = pk2((b0 * ca_0 + a0 * sa_0) * sc, (b1 * ca_1 + a1 * sa_1) * sc);
;                 o1[e] = pk2((e0 * cb_0 - f0 * sb_0) * sc, (e1 * cb_1 - f1 * sb_1) * sc);
;                 o3[e] = pk2((f0 * cb_0 + e0 * sb_0) * sc, (f1 * cb_1 + e1 * sb_1) * sc);
;             }
;             qf[0] = __builtin_bit_cast(bf16x8, o0); qf[1] = __builtin_bit_cast(bf16x8, o1); qf[2] = __builtin_bit_cast(bf16x8, o2); qf[3] = __builtin_bit_cast(bf16x8, o3);
;         }
.LBB0_1739:
	s_bfe_u32 s2, s1, 0x20004
	s_ashr_i32 s1, s0, 31
	s_lshl_b64 s[0:1], s[0:1], 12
	v_ashrrev_i32_e32 v59, 31, v58
	v_lshl_add_u64 v[108:109], s[0:1], 0, v[58:59]
	v_mov_b64_e32 v[34:35], s[92:93]
	v_cvt_f32_f16_sdwa v37, v26 dst_sel:DWORD dst_unused:UNUSED_PAD src0_sel:WORD_1
	v_cvt_f32_f16_e32 v36, v26
	v_mad_u64_u32 v[174:175], s[0:1], v108, s8, v[34:35]
	v_cvt_f32_f16_sdwa v35, v30 dst_sel:DWORD dst_unused:UNUSED_PAD src0_sel:WORD_1
	v_cvt_f32_f16_e32 v34, v30
	v_lshlrev_b32_e32 v38, 16, v10
	v_and_b32_e32 v39, 0xffff0000, v10
	v_lshlrev_b32_e32 v40, 16, v14
	v_and_b32_e32 v41, 0xffff0000, v14
	v_pk_mul_f32 v[42:43], v[40:41], v[36:37]
	v_pk_mul_f32 v[36:37], v[38:39], v[36:37]
	v_pk_fma_f32 v[42:43], v[38:39], v[34:35], v[42:43] neg_lo:[0,0,1] neg_hi:[0,0,1]
	v_pk_fma_f32 v[34:35], v[40:41], v[34:35], v[36:37]
	v_cvt_f32_f16_sdwa v37, v18 dst_sel:DWORD dst_unused:UNUSED_PAD src0_sel:WORD_1
	v_pk_mul_f32 v[34:35], v[34:35], s[72:73] op_sel_hi:[1,0]
	v_cvt_f32_f16_e32 v36, v18
	v_cvt_pk_bf16_f32 v150, v34, v35
	v_cvt_f32_f16_sdwa v35, v22 dst_sel:DWORD dst_unused:UNUSED_PAD src0_sel:WORD_1
	v_cvt_f32_f16_e32 v34, v22
	v_pk_mul_f32 v[42:43], v[42:43], s[72:73] op_sel_hi:[1,0]
	v_lshlrev_b32_e32 v38, 16, v2
	v_and_b32_e32 v39, 0xffff0000, v2
	v_lshlrev_b32_e32 v40, 16, v6
	v_and_b32_e32 v41, 0xffff0000, v6
	v_cvt_pk_bf16_f32 v224, v42, v43
	v_pk_mul_f32 v[42:43], v[40:41], v[36:37]
	v_pk_mul_f32 v[36:37], v[38:39], v[36:37]
	v_pk_fma_f32 v[42:43], v[38:39], v[34:35], v[42:43] neg_lo:[0,0,1] neg_hi:[0,0,1]
	v_pk_fma_f32 v[34:35], v[40:41], v[34:35], v[36:37]
	v_cvt_f32_f16_e32 v30, v27
	v_pk_mul_f32 v[34:35], v[34:35], s[72:73] op_sel_hi:[1,0]
	v_lshlrev_b32_e32 v14, 16, v15
	v_cvt_pk_bf16_f32 v154, v34, v35
	v_cvt_f32_f16_sdwa v35, v31 dst_sel:DWORD dst_unused:UNUSED_PAD src0_sel:WORD_1
	v_cvt_f32_f16_e32 v34, v31
	v_cvt_f32_f16_sdwa v31, v27 dst_sel:DWORD dst_unused:UNUSED_PAD src0_sel:WORD_1
	v_and_b32_e32 v15, 0xffff0000, v15
	v_lshlrev_b32_e32 v10, 16, v11
	v_and_b32_e32 v11, 0xffff0000, v11
	v_pk_mul_f32 v[26:27], v[14:15], v[30:31]
	v_lshlrev_b32_e32 v6, 16, v7
	v_pk_fma_f32 v[26:27], v[10:11], v[34:35], v[26:27] neg_lo:[0,0,1] neg_hi:[0,0,1]
	v_pk_mul_f32 v[10:11], v[10:11], v[30:31]
	v_and_b32_e32 v7, 0xffff0000, v7
	v_pk_fma_f32 v[10:11], v[14:15], v[34:35], v[10:11]
	v_cvt_f32_f16_sdwa v15, v19 dst_sel:DWORD dst_unused:UNUSED_PAD src0_sel:WORD_1
	v_pk_mul_f32 v[10:11], v[10:11], s[72:73] op_sel_hi:[1,0]
	v_cvt_f32_f16_e32 v14, v19
	v_cvt_pk_bf16_f32 v151, v10, v11
	v_cvt_f32_f16_sdwa v11, v23 dst_sel:DWORD dst_unused:UNUSED_PAD src0_sel:WORD_1
	v_cvt_f32_f16_e32 v10, v23
	v_lshlrev_b32_e32 v2, 16, v3
	v_and_b32_e32 v3, 0xffff0000, v3
	v_pk_mul_f32 v[18:19], v[6:7], v[14:15]
	v_pk_mul_f32 v[26:27], v[26:27], s[72:73] op_sel_hi:[1,0]
	v_pk_fma_f32 v[18:19], v[2:3], v[10:11], v[18:19] neg_lo:[0,0,1] neg_hi:[0,0,1]
	v_pk_mul_f32 v[2:3], v[2:3], v[14:15]
	v_pk_mul_f32 v[18:19], v[18:19], s[72:73] op_sel_hi:[1,0]
	v_pk_fma_f32 v[2:3], v[6:7], v[10:11], v[2:3]
	v_cvt_f32_f16_sdwa v7, v28 dst_sel:DWORD dst_unused:UNUSED_PAD src0_sel:WORD_1
	v_pk_mul_f32 v[2:3], v[2:3], s[72:73] op_sel_hi:[1,0]
	v_cvt_f32_f16_e32 v6, v28
	v_cvt_pk_bf16_f32 v155, v2, v3
	v_cvt_f32_f16_sdwa v3, v32 dst_sel:DWORD dst_unused:UNUSED_PAD src0_sel:WORD_1
	v_cvt_f32_f16_e32 v2, v32
	v_lshlrev_b32_e32 v14, 16, v16
	v_and_b32_e32 v15, 0xffff0000, v16
	v_cvt_pk_bf16_f32 v229, v18, v19
	v_lshlrev_b32_e32 v10, 16, v12
	v_and_b32_e32 v11, 0xffff0000, v12
	v_pk_mul_f32 v[18:19], v[14:15], v[6:7]
	v_cvt_pk_bf16_f32 v225, v26, v27
	v_pk_fma_f32 v[18:19], v[10:11], v[2:3], v[18:19] neg_lo:[0,0,1] neg_hi:[0,0,1]
	v_cvt_f32_f16_sdwa v23, v29 dst_sel:DWORD dst_unused:UNUSED_PAD src0_sel:WORD_1
	v_cvt_f32_f16_e32 v22, v29
	ds_read_b128 v[26:29], v216
	v_pk_mul_f32 v[18:19], v[18:19], s[72:73] op_sel_hi:[1,0]
	v_lshlrev_b32_e32 v16, 16, v17
	v_cvt_pk_bf16_f32 v226, v18, v19
	v_cvt_f32_f16_sdwa v19, v33 dst_sel:DWORD dst_unused:UNUSED_PAD src0_sel:WORD_1
	v_cvt_f32_f16_e32 v18, v33
	v_and_b32_e32 v17, 0xffff0000, v17
	v_pk_mul_f32 v[6:7], v[10:11], v[6:7]
	v_lshlrev_b32_e32 v30, 16, v13
	v_and_b32_e32 v31, 0xffff0000, v13
	v_pk_mul_f32 v[10:11], v[16:17], v[22:23]
	v_pk_fma_f32 v[2:3], v[14:15], v[2:3], v[6:7]
	v_pk_fma_f32 v[10:11], v[30:31], v[18:19], v[10:11] neg_lo:[0,0,1] neg_hi:[0,0,1]
	v_pk_mul_f32 v[42:43], v[42:43], s[72:73] op_sel_hi:[1,0]
	v_pk_mul_f32 v[10:11], v[10:11], s[72:73] op_sel_hi:[1,0]
	v_pk_mul_f32 v[2:3], v[2:3], s[72:73] op_sel_hi:[1,0]
	v_cvt_pk_bf16_f32 v227, v10, v11
	v_cvt_f32_f16_sdwa v7, v20 dst_sel:DWORD dst_unused:UNUSED_PAD src0_sel:WORD_1
	v_cvt_f32_f16_e32 v6, v20
	s_waitcnt lgkmcnt(0)
	v_mfma_f32_32x32x16_bf16 v[66:81], v[26:29], v[224:227], 0
	ds_read_b128 v[10:13], v216 offset:4096
	v_cvt_pk_bf16_f32 v228, v42, v43
	v_cvt_pk_bf16_f32 v152, v2, v3
	v_cvt_f32_f16_sdwa v3, v24 dst_sel:DWORD dst_unused:UNUSED_PAD src0_sel:WORD_1
	v_cvt_f32_f16_e32 v2, v24
	v_lshlrev_b32_e32 v14, 16, v4
	s_waitcnt lgkmcnt(0)
	v_mfma_f32_32x32x16_bf16 v[50:65], v[10:13], v[224:227], 0
	ds_read_b128 v[10:13], v216 offset:8192
	v_and_b32_e32 v15, 0xffff0000, v4
	v_lshlrev_b32_e32 v26, 16, v8
	v_and_b32_e32 v27, 0xffff0000, v8
	v_pk_mul_f32 v[28:29], v[26:27], v[6:7]
	v_pk_mul_f32 v[6:7], v[14:15], v[6:7]
	s_waitcnt lgkmcnt(0)
; #define LASP __attribute__((address_space(3)))
; __device__ __forceinline__ void attn_phase_mfma(const Ctx& c, unsigned char* lds_raw, bool do_store) {
;     ...
;         for (int kb = 0; kb < 5; ++kb)
;     #pragma unroll
;             for (int e = 0; e < 16; ++e) sacc[kb][e] = 0.f;
;     #pragma unroll
;         for (int s4 = 0; s4 < 4; ++s4) {
;     #pragma unroll
;             for (int kb = 0; kb < 5; ++kb) {
;                 const int row = 32 * wave + 32 * kb + rq;
;                 const bf16x8 kf = *(const LASP bf16x8*)(Kt + row * 128 + (((2 * s4 + h) ^ (row & 7)) << 4));
;                 sacc[kb] = mfma32_g(kf, qf[s4], sacc[kb]);
;             }
;             __builtin_amdgcn_sched_barrier(0);
;         }
;         asm volatile("s_nop 15\n\ts_nop 15" : "+v"(sacc[0]), "+v"(sacc[1]), "+v"(sacc[2]), "+v"(sacc[3]), "+v"(sacc[4]));
;         const int jbase = i0 - 64 + 32 * wave;
;         float mx = -1e30f;
;     #pragma unroll
;         for (int kb = 0; kb < 5; ++kb)
;     #pragma unroll
;             for (int e = 0; e < 16; ++e) {
;                 const int row = (e & 3) + 8 * (e >> 2) + 4 * h, rel = 32 * kb + row - rq, j = jbase + 32 * kb + row;
;                 const bool valid = (rel >= 0) && (rel <= 128) && (j >= 0) && (j < L);
;                 const float sv = valid ? sacc[kb][e] : -1e30f;
;                 sacc[kb][e] = sv; mx = fmaxf(mx, sv);
	v_mfma_f32_32x32x16_bf16 v[34:49], v[10:13], v[224:227], 0
	ds_read_b128 v[10:13], v216 offset:12288
	v_pk_fma_f32 v[28:29], v[14:15], v[2:3], v[28:29] neg_lo:[0,0,1] neg_hi:[0,0,1]
	v_pk_fma_f32 v[2:3], v[26:27], v[2:3], v[6:7]
	v_pk_mul_f32 v[28:29], v[28:29], s[72:73] op_sel_hi:[1,0]
	v_pk_mul_f32 v[2:3], v[2:3], s[72:73] op_sel_hi:[1,0]
	v_cvt_pk_bf16_f32 v230, v28, v29
	v_cvt_pk_bf16_f32 v156, v2, v3
	v_pk_mul_f32 v[2:3], v[30:31], v[22:23]
	v_cvt_f32_f16_sdwa v7, v21 dst_sel:DWORD dst_unused:UNUSED_PAD src0_sel:WORD_1
	v_pk_fma_f32 v[2:3], v[16:17], v[18:19], v[2:3]
	v_cvt_f32_f16_e32 v6, v21
	v_pk_mul_f32 v[2:3], v[2:3], s[72:73] op_sel_hi:[1,0]
	v_lshlrev_b32_e32 v8, 16, v9
	v_cvt_pk_bf16_f32 v153, v2, v3
	v_cvt_f32_f16_sdwa v3, v25 dst_sel:DWORD dst_unused:UNUSED_PAD src0_sel:WORD_1
	v_cvt_f32_f16_e32 v2, v25
	s_waitcnt lgkmcnt(0)
	v_mfma_f32_32x32x16_bf16 v[18:33], v[10:13], v[224:227], 0
	ds_read_b128 v[232:235], v216 offset:16384
	v_and_b32_e32 v9, 0xffff0000, v9
	v_lshlrev_b32_e32 v4, 16, v5
	v_and_b32_e32 v5, 0xffff0000, v5
	v_pk_mul_f32 v[14:15], v[8:9], v[6:7]
	s_lshl_b32 s0, s88, 8
	s_lshl_b32 s1, s2, 6
	v_pk_fma_f32 v[14:15], v[4:5], v[2:3], v[14:15] neg_lo:[0,0,1] neg_hi:[0,0,1]
	v_pk_mul_f32 v[4:5], v[4:5], v[6:7]
	s_or_b32 s0, s1, s0
	v_pk_fma_f32 v[2:3], v[8:9], v[2:3], v[4:5]
	v_mad_i32_i24 v175, v109, s8, v175
	s_ashr_i32 s1, s0, 31
	v_pk_mul_f32 v[10:11], v[14:15], s[72:73] op_sel_hi:[1,0]
	v_pk_mul_f32 v[2:3], v[2:3], s[72:73] op_sel_hi:[1,0]
	v_cvt_pk_bf16_f32 v231, v10, v11
	v_cvt_pk_bf16_f32 v157, v2, v3
	s_lshr_b32 s3, 0x1000, s96
	v_lshl_add_u64 v[174:175], s[0:1], 1, v[174:175]
	s_waitcnt lgkmcnt(0)
	v_mfma_f32_32x32x16_bf16 v[2:17], v[232:235], v[224:227], 0
	ds_read_b128 v[224:227], v217
	s_waitcnt lgkmcnt(0)
	v_mfma_f32_32x32x16_bf16 v[66:81], v[224:227], v[228:231], v[66:81]
	ds_read_b128 v[224:227], v217 offset:4096
	s_waitcnt lgkmcnt(0)
	v_mfma_f32_32x32x16_bf16 v[50:65], v[224:227], v[228:231], v[50:65]
	ds_read_b128 v[224:227], v217 offset:8192
	s_waitcnt lgkmcnt(0)
	v_mfma_f32_32x32x16_bf16 v[34:49], v[224:227], v[228:231], v[34:49]
	ds_read_b128 v[224:227], v217 offset:12288
	s_waitcnt lgkmcnt(0)
	v_mfma_f32_32x32x16_bf16 v[18:33], v[224:227], v[228:231], v[18:33]
	ds_read_b128 v[224:227], v217 offset:16384
	s_waitcnt lgkmcnt(0)
	v_mfma_f32_32x32x16_bf16 v[2:17], v[224:227], v[228:231], v[2:17]
	ds_read_b128 v[224:227], v218
	s_waitcnt lgkmcnt(0)
	v_mfma_f32_32x32x16_bf16 v[66:81], v[224:227], v[150:153], v[66:81]
	ds_read_b128 v[224:227], v218 offset:4096
	s_waitcnt lgkmcnt(0)
	v_mfma_f32_32x32x16_bf16 v[50:65], v[224:227], v[150:153], v[50:65]
	ds_read_b128 v[224:227], v218 offset:8192
	s_waitcnt lgkmcnt(0)
	v_mfma_f32_32x32x16_bf16 v[34:49], v[224:227], v[150:153], v[34:49]
	ds_read_b128 v[224:227], v218 offset:12288
	s_waitcnt lgkmcnt(0)
	v_mfma_f32_32x32x16_bf16 v[18:33], v[224:227], v[150:153], v[18:33]
	ds_read_b128 v[224:227], v218 offset:16384
	s_waitcnt lgkmcnt(0)
	v_mfma_f32_32x32x16_bf16 v[2:17], v[224:227], v[150:153], v[2:17]
	ds_read_b128 v[150:153], v219
	s_waitcnt lgkmcnt(0)
	v_mfma_f32_32x32x16_bf16 v[66:81], v[150:153], v[154:157], v[66:81]
	ds_read_b128 v[150:153], v219 offset:4096
	s_waitcnt lgkmcnt(0)
	v_mfma_f32_32x32x16_bf16 v[50:65], v[150:153], v[154:157], v[50:65]
	ds_read_b128 v[150:153], v219 offset:8192
	s_waitcnt lgkmcnt(0)
	v_mfma_f32_32x32x16_bf16 v[34:49], v[150:153], v[154:157], v[34:49]
	ds_read_b128 v[150:153], v219 offset:12288
	s_waitcnt lgkmcnt(0)
	v_mfma_f32_32x32x16_bf16 v[18:33], v[150:153], v[154:157], v[18:33]
	ds_read_b128 v[150:153], v219 offset:16384
	s_waitcnt lgkmcnt(0)
	v_mfma_f32_32x32x16_bf16 v[2:17], v[150:153], v[154:157], v[2:17]
	s_add_i32 s0, s89, s73
	s_cmp_gt_i32 s0, -1
	v_readlane_b32 s12, v255, 17
	s_cselect_b64 s[10:11], -1, 0
	v_or_b32_e32 v107, s0, v166
	v_readlane_b32 s13, v255, 18
	s_and_b64 s[12:13], s[12:13], s[10:11]
	v_cmp_gt_i32_e32 vcc, s3, v107
	s_nop 15
	s_nop 15
	s_and_b64 vcc, s[12:13], vcc
	v_readlane_b32 s12, v255, 19
	v_cndmask_b32_e32 v107, v222, v66, vcc
	v_or_b32_e32 v66, s0, v184
	v_readlane_b32 s13, v255, 20
	s_and_b64 s[12:13], s[12:13], s[10:11]
	v_cmp_gt_i32_e32 vcc, s3, v66
	s_and_b64 vcc, s[12:13], vcc
	v_readlane_b32 s12, v255, 21
	v_or_b32_e32 v150, s0, v185
	v_readlane_b32 s13, v255, 22
	v_cndmask_b32_e32 v67, v222, v67, vcc
	s_and_b64 s[12:13], s[12:13], s[10:11]
	v_cmp_gt_i32_e32 vcc, s3, v150
	s_and_b64 vcc, s[12:13], vcc
	v_readlane_b32 s12, v255, 23
	v_or_b32_e32 v150, s0, v186
	v_readlane_b32 s13, v255, 24
	v_cndmask_b32_e32 v68, v222, v68, vcc
	s_and_b64 s[12:13], s[12:13], s[10:11]
	v_cmp_gt_i32_e32 vcc, s3, v150
	s_and_b64 vcc, s[12:13], vcc
	v_or_b32_e32 v150, s0, v187
	v_cndmask_b32_e32 v69, v222, v69, vcc
	s_and_b64 s[12:13], s[14:15], s[10:11]
	v_cmp_gt_i32_e32 vcc, s3, v150
	s_and_b64 vcc, s[12:13], vcc
	v_or_b32_e32 v150, s0, v188
	v_cndmask_b32_e32 v70, v222, v70, vcc
	s_and_b64 s[12:13], s[16:17], s[10:11]
	v_cmp_gt_i32_e32 vcc, s3, v150
	s_and_b64 vcc, s[12:13], vcc
	v_or_b32_e32 v150, s0, v189
	v_cndmask_b32_e32 v71, v222, v71, vcc
	s_and_b64 s[12:13], s[18:19], s[10:11]
	v_cmp_gt_i32_e32 vcc, s3, v150
	s_and_b64 vcc, s[12:13], vcc
	v_or_b32_e32 v150, s0, v190
	v_cndmask_b32_e32 v72, v222, v72, vcc
	s_and_b64 s[12:13], s[20:21], s[10:11]
	v_cmp_gt_i32_e32 vcc, s3, v150
	s_and_b64 vcc, s[12:13], vcc
	v_or_b32_e32 v150, s0, v191
	v_cndmask_b32_e32 v73, v222, v73, vcc
	s_and_b64 s[12:13], s[22:23], s[10:11]
	v_cmp_gt_i32_e32 vcc, s3, v150
	s_and_b64 vcc, s[12:13], vcc
	v_or_b32_e32 v150, s0, v192
	v_cndmask_b32_e32 v74, v222, v74, vcc
	s_and_b64 s[12:13], s[24:25], s[10:11]
; __device__ __forceinline__ void attn_phase_mfma(const Ctx& c, unsigned char* lds_raw, bool do_store) {
;     ...
;         const int jbase = i0 - 64 + 32 * wave;
;         float mx = -1e30f;
;     #pragma unroll
;         for (int kb = 0; kb < 5; ++kb)
;     #pragma unroll
;             for (int e = 0; e < 16; ++e) {
;                 const int row = (e & 3) + 8 * (e >> 2) + 4 * h, rel = 32 * kb + row - rq, j = jbase + 32 * kb + row;
;                 const bool valid = (rel >= 0) && (rel <= 128) && (j >= 0) && (j < L);
;                 const float sv = valid ? sacc[kb][e] : -1e30f;
;                 sacc[kb][e] = sv; mx = fmaxf(mx, sv);
;             }
	v_cmp_gt_i32_e32 vcc, s3, v150
	s_and_b64 vcc, s[12:13], vcc
	v_or_b32_e32 v150, s0, v193
	v_cndmask_b32_e32 v75, v222, v75, vcc
	s_and_b64 s[12:13], s[26:27], s[10:11]
	v_cmp_gt_i32_e32 vcc, s3, v150
	s_and_b64 vcc, s[12:13], vcc
	v_or_b32_e32 v150, s0, v194
	v_cndmask_b32_e32 v76, v222, v76, vcc
	s_and_b64 s[12:13], s[28:29], s[10:11]
	v_cmp_gt_i32_e32 vcc, s3, v150
	s_and_b64 vcc, s[12:13], vcc
	v_or_b32_e32 v150, s0, v195
	v_cndmask_b32_e32 v77, v222, v77, vcc
	s_and_b64 s[12:13], s[30:31], s[10:11]
	v_cmp_gt_i32_e32 vcc, s3, v150
	s_and_b64 vcc, s[12:13], vcc
	v_or_b32_e32 v150, s0, v196
	v_cndmask_b32_e32 v78, v222, v78, vcc
	s_and_b64 s[12:13], s[34:35], s[10:11]
	v_cmp_gt_i32_e32 vcc, s3, v150
	s_and_b64 vcc, s[12:13], vcc
	v_or_b32_e32 v150, s0, v197
	v_cndmask_b32_e32 v79, v222, v79, vcc
	s_and_b64 s[12:13], s[36:37], s[10:11]
	v_cmp_gt_i32_e32 vcc, s3, v150
	s_and_b64 vcc, s[12:13], vcc
	v_or_b32_e32 v150, s0, v198
	s_mov_b32 s1, 0xf149f2ca
	v_cndmask_b32_e32 v80, v222, v80, vcc
	s_and_b64 s[10:11], s[38:39], s[10:11]
	v_cmp_gt_i32_e32 vcc, s3, v150
	v_max3_f32 v66, v107, s1, v67
	s_and_b64 vcc, s[10:11], vcc
	s_add_i32 s1, s0, 32
	s_cmpk_gt_i32 s0, 0xffdf
	v_or_b32_e32 v150, s1, v166
	v_cndmask_b32_e32 v81, v222, v81, vcc
	s_cselect_b64 s[10:11], -1, 0
	v_cmp_gt_i32_e32 vcc, s3, v150
	s_and_b64 vcc, s[10:11], vcc
	s_add_i32 s9, s9, s73
	v_cndmask_b32_e32 v150, v222, v50, vcc
	v_or_b32_e32 v50, s1, v184
	v_cmp_gt_i32_e32 vcc, s3, v50
	s_and_b64 vcc, s[10:11], vcc
	v_max3_f32 v66, v66, v68, v69
	v_cndmask_b32_e32 v151, v222, v51, vcc
	v_or_b32_e32 v51, s1, v185
	v_cmp_gt_i32_e32 vcc, s3, v51
	s_and_b64 vcc, s[10:11], vcc
	v_or_b32_e32 v51, s1, v186
	v_cndmask_b32_e32 v152, v222, v52, vcc
	v_cmp_gt_i32_e32 vcc, s3, v51
	s_and_b64 vcc, s[10:11], vcc
	v_or_b32_e32 v51, s1, v187
	v_cndmask_b32_e32 v153, v222, v53, vcc
	v_cmp_gt_i32_e32 vcc, s3, v51
	s_and_b64 vcc, s[10:11], vcc
	v_or_b32_e32 v51, s1, v188
	v_cndmask_b32_e32 v154, v222, v54, vcc
	v_cmp_gt_i32_e32 vcc, s3, v51
	s_and_b64 vcc, s[10:11], vcc
	v_or_b32_e32 v51, s1, v189
	v_cndmask_b32_e32 v155, v222, v55, vcc
	v_cmp_gt_i32_e32 vcc, s3, v51
	s_and_b64 vcc, s[10:11], vcc
	v_or_b32_e32 v51, s1, v190
	v_cndmask_b32_e32 v156, v222, v56, vcc
	v_cmp_gt_i32_e32 vcc, s3, v51
	s_and_b64 vcc, s[10:11], vcc
	v_or_b32_e32 v51, s1, v191
	v_cndmask_b32_e32 v157, v222, v57, vcc
	v_cmp_gt_i32_e32 vcc, s3, v51
	s_and_b64 vcc, s[10:11], vcc
	v_or_b32_e32 v51, s1, v192
	v_cndmask_b32_e32 v159, v222, v58, vcc
	v_cmp_gt_i32_e32 vcc, s3, v51
	s_and_b64 vcc, s[10:11], vcc
	v_or_b32_e32 v51, s1, v193
	v_cndmask_b32_e32 v169, v222, v59, vcc
	v_cmp_gt_i32_e32 vcc, s3, v51
	s_and_b64 vcc, s[10:11], vcc
	v_or_b32_e32 v51, s1, v194
	v_cndmask_b32_e32 v224, v222, v60, vcc
	v_cmp_gt_i32_e32 vcc, s3, v51
	s_and_b64 vcc, s[10:11], vcc
	v_or_b32_e32 v51, s1, v195
	v_cndmask_b32_e32 v225, v222, v61, vcc
	v_cmp_gt_i32_e32 vcc, s3, v51
	s_and_b64 vcc, s[10:11], vcc
	v_or_b32_e32 v51, s1, v196
	v_cndmask_b32_e32 v226, v222, v62, vcc
	v_cmp_gt_i32_e32 vcc, s3, v51
	s_and_b64 vcc, s[10:11], vcc
	v_or_b32_e32 v51, s1, v197
	v_cndmask_b32_e32 v227, v222, v63, vcc
	v_cmp_gt_i32_e32 vcc, s3, v51
	s_and_b64 vcc, s[10:11], vcc
	v_or_b32_e32 v51, s1, v198
	v_cndmask_b32_e32 v228, v222, v64, vcc
	v_cmp_gt_i32_e32 vcc, s3, v51
	s_and_b64 vcc, s[10:11], vcc
	s_cmp_gt_i32 s9, -1
	v_or_b32_e32 v51, s9, v166
	v_cndmask_b32_e32 v229, v222, v65, vcc
	s_cselect_b64 s[10:11], -1, 0
	v_cmp_gt_i32_e32 vcc, s3, v51
	s_and_b64 vcc, s[10:11], vcc
	s_add_i32 s1, s0, 0x60
	v_cndmask_b32_e32 v230, v222, v34, vcc
	v_or_b32_e32 v34, s9, v184
	v_cmp_gt_i32_e32 vcc, s3, v34
	s_and_b64 vcc, s[10:11], vcc
	v_max3_f32 v66, v66, v70, v71
	v_cndmask_b32_e32 v231, v222, v35, vcc
	v_or_b32_e32 v35, s9, v185
	v_cmp_gt_i32_e32 vcc, s3, v35
	s_and_b64 vcc, s[10:11], vcc
	v_or_b32_e32 v35, s9, v186
	v_cndmask_b32_e32 v232, v222, v36, vcc
	v_cmp_gt_i32_e32 vcc, s3, v35
	s_and_b64 vcc, s[10:11], vcc
	v_or_b32_e32 v35, s9, v187
	v_cndmask_b32_e32 v233, v222, v37, vcc
	v_cmp_gt_i32_e32 vcc, s3, v35
	s_and_b64 vcc, s[10:11], vcc
	v_or_b32_e32 v35, s9, v188
	v_cndmask_b32_e32 v234, v222, v38, vcc
	v_cmp_gt_i32_e32 vcc, s3, v35
	s_and_b64 vcc, s[10:11], vcc
	v_or_b32_e32 v35, s9, v189
	v_cndmask_b32_e32 v235, v222, v39, vcc
	v_cmp_gt_i32_e32 vcc, s3, v35
	s_and_b64 vcc, s[10:11], vcc
	v_or_b32_e32 v35, s9, v190
	v_cndmask_b32_e32 v236, v222, v40, vcc
	v_cmp_gt_i32_e32 vcc, s3, v35
	s_and_b64 vcc, s[10:11], vcc
	v_or_b32_e32 v35, s9, v191
	v_cndmask_b32_e32 v237, v222, v41, vcc
	v_cmp_gt_i32_e32 vcc, s3, v35
	s_and_b64 vcc, s[10:11], vcc
	v_or_b32_e32 v35, s9, v192
	v_cndmask_b32_e32 v238, v222, v42, vcc
	v_cmp_gt_i32_e32 vcc, s3, v35
	s_and_b64 vcc, s[10:11], vcc
	v_or_b32_e32 v35, s9, v193
	v_cndmask_b32_e32 v239, v222, v43, vcc
	v_cmp_gt_i32_e32 vcc, s3, v35
	s_and_b64 vcc, s[10:11], vcc
	v_or_b32_e32 v35, s9, v194
	v_cndmask_b32_e32 v240, v222, v44, vcc
	v_cmp_gt_i32_e32 vcc, s3, v35
	s_and_b64 vcc, s[10:11], vcc
	v_or_b32_e32 v35, s9, v195
	v_cndmask_b32_e32 v241, v222, v45, vcc
	v_cmp_gt_i32_e32 vcc, s3, v35
	s_and_b64 vcc, s[10:11], vcc
	v_or_b32_e32 v35, s9, v196
	v_cndmask_b32_e32 v242, v222, v46, vcc
	v_cmp_gt_i32_e32 vcc, s3, v35
	s_and_b64 vcc, s[10:11], vcc
	v_or_b32_e32 v35, s9, v197
	v_cndmask_b32_e32 v243, v222, v47, vcc
	v_cmp_gt_i32_e32 vcc, s3, v35
	s_and_b64 vcc, s[10:11], vcc
	v_or_b32_e32 v35, s9, v198
	v_cndmask_b32_e32 v244, v222, v48, vcc
	v_cmp_gt_i32_e32 vcc, s3, v35
	s_and_b64 vcc, s[10:11], vcc
	s_cmpk_gt_i32 s0, 0xff9f
	v_or_b32_e32 v35, s1, v166
	v_cndmask_b32_e32 v245, v222, v49, vcc
	s_cselect_b64 s[10:11], -1, 0
; __device__ __forceinline__ void attn_phase_mfma(const Ctx& c, unsigned char* lds_raw, bool do_store) {
;     ...
;     #pragma unroll
;         for (int kb = 0; kb < 5; ++kb)
;     #pragma unroll
;             for (int e = 0; e < 16; ++e) {
;                 const int row = (e & 3) + 8 * (e >> 2) + 4 * h, rel = 32 * kb + row - rq, j = jbase + 32 * kb + row;
;                 const bool valid = (rel >= 0) && (rel <= 128) && (j >= 0) && (j < L);
;                 const float sv = valid ? sacc[kb][e] : -1e30f;
;                 sacc[kb][e] = sv; mx = fmaxf(mx, sv);
;             }
;         mx = fmaxf(mx, __shfl_xor(mx, 32));
	v_cmp_gt_i32_e32 vcc, s3, v35
	s_and_b64 vcc, s[10:11], vcc
	v_max3_f32 v66, v66, v72, v73
	v_cndmask_b32_e32 v246, v222, v18, vcc
	v_or_b32_e32 v18, s1, v184
	v_cmp_gt_i32_e32 vcc, s3, v18
	v_max3_f32 v66, v66, v74, v75
	s_and_b64 vcc, s[10:11], vcc
	v_max3_f32 v66, v66, v76, v77
	v_cndmask_b32_e32 v65, v222, v19, vcc
	v_or_b32_e32 v19, s1, v185
	v_max3_f32 v66, v66, v78, v79
	v_cmp_gt_i32_e32 vcc, s3, v19
	v_max3_f32 v66, v66, v80, v81
	s_and_b64 vcc, s[10:11], vcc
	v_or_b32_e32 v19, s1, v186
	v_max3_f32 v50, v66, v150, v151
	v_cndmask_b32_e32 v66, v222, v20, vcc
	v_cmp_gt_i32_e32 vcc, s3, v19
	s_and_b64 vcc, s[10:11], vcc
	v_or_b32_e32 v19, s1, v187
	v_cndmask_b32_e32 v63, v222, v21, vcc
	v_cmp_gt_i32_e32 vcc, s3, v19
	s_and_b64 vcc, s[10:11], vcc
	v_or_b32_e32 v19, s1, v188
	v_cndmask_b32_e32 v64, v222, v22, vcc
	v_cmp_gt_i32_e32 vcc, s3, v19
	s_and_b64 vcc, s[10:11], vcc
	v_or_b32_e32 v19, s1, v189
	v_cndmask_b32_e32 v61, v222, v23, vcc
	v_cmp_gt_i32_e32 vcc, s3, v19
	s_and_b64 vcc, s[10:11], vcc
	v_or_b32_e32 v19, s1, v190
	v_cndmask_b32_e32 v62, v222, v24, vcc
	v_cmp_gt_i32_e32 vcc, s3, v19
	s_and_b64 vcc, s[10:11], vcc
	v_or_b32_e32 v19, s1, v191
	v_cndmask_b32_e32 v59, v222, v25, vcc
	v_cmp_gt_i32_e32 vcc, s3, v19
	s_and_b64 vcc, s[10:11], vcc
	v_or_b32_e32 v19, s1, v192
	v_cndmask_b32_e32 v60, v222, v26, vcc
	v_cmp_gt_i32_e32 vcc, s3, v19
	s_and_b64 vcc, s[10:11], vcc
	v_or_b32_e32 v19, s1, v193
	v_cndmask_b32_e32 v57, v222, v27, vcc
	v_cmp_gt_i32_e32 vcc, s3, v19
	s_and_b64 vcc, s[10:11], vcc
	v_or_b32_e32 v19, s1, v194
	v_cndmask_b32_e32 v58, v222, v28, vcc
	v_cmp_gt_i32_e32 vcc, s3, v19
	s_and_b64 vcc, s[10:11], vcc
	v_or_b32_e32 v19, s1, v195
	v_cndmask_b32_e32 v55, v222, v29, vcc
	v_cmp_gt_i32_e32 vcc, s3, v19
	s_and_b64 vcc, s[10:11], vcc
	v_or_b32_e32 v19, s1, v196
	v_cndmask_b32_e32 v56, v222, v30, vcc
	v_cmp_gt_i32_e32 vcc, s3, v19
	s_and_b64 vcc, s[10:11], vcc
	v_or_b32_e32 v19, s1, v197
	v_cndmask_b32_e32 v53, v222, v31, vcc
	v_cmp_gt_i32_e32 vcc, s3, v19
	s_and_b64 vcc, s[10:11], vcc
	v_or_b32_e32 v19, s1, v198
	v_cndmask_b32_e32 v54, v222, v32, vcc
	v_cmp_gt_i32_e32 vcc, s3, v19
	s_and_b64 vcc, s[10:11], vcc
	s_add_i32 s9, s0, 0x80
	s_cmpk_gt_i32 s0, 0xff7f
	s_cselect_b64 s[0:1], -1, 0
	v_or_b32_e32 v19, s9, v166
	v_cndmask_b32_e32 v51, v222, v33, vcc
	s_and_b64 s[10:11], s[40:41], s[0:1]
	v_cmp_gt_i32_e32 vcc, s3, v19
	v_max3_f32 v50, v50, v152, v153
	s_and_b64 vcc, s[10:11], vcc
	v_max3_f32 v50, v50, v154, v155
	v_cndmask_b32_e32 v52, v222, v2, vcc
	v_or_b32_e32 v2, s9, v184
	v_max3_f32 v50, v50, v156, v157
	s_and_b64 s[10:11], s[42:43], s[0:1]
	v_cmp_gt_i32_e32 vcc, s3, v2
	v_max3_f32 v50, v50, v159, v169
	s_and_b64 vcc, s[10:11], vcc
	v_max3_f32 v50, v50, v224, v225
	v_cndmask_b32_e32 v49, v222, v3, vcc
	v_or_b32_e32 v3, s9, v185
	v_max3_f32 v50, v50, v226, v227
	s_and_b64 s[10:11], s[44:45], s[0:1]
	v_cmp_gt_i32_e32 vcc, s3, v3
	v_max3_f32 v50, v50, v228, v229
	s_and_b64 vcc, s[10:11], vcc
	v_or_b32_e32 v3, s9, v186
	v_max3_f32 v34, v50, v230, v231
	v_cndmask_b32_e32 v50, v222, v4, vcc
	s_and_b64 s[10:11], s[46:47], s[0:1]
	v_cmp_gt_i32_e32 vcc, s3, v3
	s_and_b64 vcc, s[10:11], vcc
	v_or_b32_e32 v3, s9, v187
	v_cndmask_b32_e32 v47, v222, v5, vcc
	s_and_b64 s[10:11], s[48:49], s[0:1]
	v_cmp_gt_i32_e32 vcc, s3, v3
	s_and_b64 vcc, s[10:11], vcc
	v_or_b32_e32 v3, s9, v188
	v_cndmask_b32_e32 v48, v222, v6, vcc
	s_and_b64 s[10:11], s[50:51], s[0:1]
	v_cmp_gt_i32_e32 vcc, s3, v3
	s_and_b64 vcc, s[10:11], vcc
	v_or_b32_e32 v3, s9, v189
	v_max3_f32 v34, v34, v232, v233
	v_cndmask_b32_e32 v45, v222, v7, vcc
	s_and_b64 s[10:11], s[52:53], s[0:1]
	v_cmp_gt_i32_e32 vcc, s3, v3
	v_max3_f32 v34, v34, v234, v235
	s_and_b64 vcc, s[10:11], vcc
	v_or_b32_e32 v3, s9, v190
	v_max3_f32 v34, v34, v236, v237
	v_cndmask_b32_e32 v46, v222, v8, vcc
	s_and_b64 s[10:11], s[54:55], s[0:1]
	v_cmp_gt_i32_e32 vcc, s3, v3
	v_max3_f32 v34, v34, v238, v239
	s_and_b64 vcc, s[10:11], vcc
	v_or_b32_e32 v3, s9, v191
	v_max3_f32 v34, v34, v240, v241
	v_cndmask_b32_e32 v43, v222, v9, vcc
	s_and_b64 s[10:11], s[56:57], s[0:1]
	v_cmp_gt_i32_e32 vcc, s3, v3
	v_max3_f32 v34, v34, v242, v243
	s_and_b64 vcc, s[10:11], vcc
	v_or_b32_e32 v3, s9, v192
	v_max3_f32 v34, v34, v244, v245
	v_cndmask_b32_e32 v44, v222, v10, vcc
	s_and_b64 s[10:11], s[58:59], s[0:1]
	v_cmp_gt_i32_e32 vcc, s3, v3
	v_max3_f32 v18, v34, v246, v65
	s_and_b64 vcc, s[10:11], vcc
	v_or_b32_e32 v3, s9, v193
	v_max3_f32 v18, v18, v66, v63
	v_cndmask_b32_e32 v41, v222, v11, vcc
	s_and_b64 s[10:11], s[60:61], s[0:1]
	v_cmp_gt_i32_e32 vcc, s3, v3
	v_max3_f32 v18, v18, v64, v61
	s_and_b64 vcc, s[10:11], vcc
	v_or_b32_e32 v3, s9, v194
	v_max3_f32 v18, v18, v62, v59
	v_cndmask_b32_e32 v42, v222, v12, vcc
	s_and_b64 s[10:11], s[62:63], s[0:1]
	v_cmp_gt_i32_e32 vcc, s3, v3
	v_max3_f32 v18, v18, v60, v57
	s_and_b64 vcc, s[10:11], vcc
	v_or_b32_e32 v3, s9, v195
	v_max3_f32 v18, v18, v58, v55
	v_cndmask_b32_e32 v39, v222, v13, vcc
	s_and_b64 s[10:11], s[64:65], s[0:1]
	v_cmp_gt_i32_e32 vcc, s3, v3
	v_max3_f32 v18, v18, v56, v53
	s_and_b64 vcc, s[10:11], vcc
	v_or_b32_e32 v3, s9, v196
	v_max3_f32 v18, v18, v54, v51
	v_cndmask_b32_e32 v40, v222, v14, vcc
	s_and_b64 s[10:11], s[66:67], s[0:1]
	v_cmp_gt_i32_e32 vcc, s3, v3
	v_max3_f32 v2, v18, v52, v49
	s_and_b64 vcc, s[10:11], vcc
	v_or_b32_e32 v3, s9, v197
	v_max3_f32 v2, v2, v50, v47
	v_cndmask_b32_e32 v36, v222, v15, vcc
	s_and_b64 s[10:11], s[68:69], s[0:1]
	v_cmp_gt_i32_e32 vcc, s3, v3
	v_max3_f32 v2, v2, v48, v45
	s_and_b64 vcc, s[10:11], vcc
	v_or_b32_e32 v3, s9, v198
	v_max3_f32 v2, v2, v46, v43
	v_cndmask_b32_e32 v37, v222, v16, vcc
	s_and_b64 s[0:1], s[70:71], s[0:1]
	v_cmp_gt_i32_e32 vcc, s3, v3
	v_and_b32_e32 v4, 64, v220
	v_max3_f32 v2, v2, v44, v41
	s_and_b64 vcc, s[0:1], vcc
	v_xor_b32_e32 v3, 32, v220
	v_add_u32_e32 v4, 64, v4
	v_max3_f32 v2, v2, v42, v39
	v_cndmask_b32_e32 v38, v222, v17, vcc
	v_cmp_lt_i32_e32 vcc, v3, v4
	v_max3_f32 v2, v2, v40, v36
	v_max3_f32 v2, v2, v37, v38
	v_cndmask_b32_e32 v3, v220, v3, vcc
	v_lshlrev_b32_e32 v35, 2, v3
	ds_bpermute_b32 v3, v35, v2
	s_waitcnt lgkmcnt(0)
; #define LASP __attribute__((address_space(3)))
; __device__ __forceinline__ unsigned cvtpk(float lo, float hi) { return pk2(lo, hi); }
; __device__ __forceinline__ void attn_phase_mfma(const Ctx& c, unsigned char* lds_raw, bool do_store) {
;     ...
;         float lsum = 0.f;
;     #pragma unroll
;         for (int kb = 0; kb < 5; ++kb)
;     #pragma unroll
;             for (int e = 0; e < 16; ++e) { const float p = __builtin_amdgcn_exp2f(sacc[kb][e] - mx); sacc[kb][e] = p; lsum += p; }
;         lsum += __shfl_xor(lsum, 32);
;         f32x16 oacc[2];
;     #pragma unroll
;         for (int db = 0; db < 2; ++db)
;     #pragma unroll
;             for (int e = 0; e < 16; ++e) oacc[db][e] = 0.f;
;     #pragma unroll
;         for (int kb = 0; kb < 5; ++kb)
;     #pragma unroll
;             for (int s2 = 0; s2 < 2; ++s2) {
;                 u32x4 pw;
;     #pragma unroll
;                 for (int e = 0; e < 4; ++e) pw[e] = cvtpk(sacc[kb][8 * s2 + 2 * e], sacc[kb][8 * s2 + 2 * e + 1]);
;                 const bf16x8 pf = __builtin_bit_cast(bf16x8, pw);
;                 const int kp = (32 * wave + 32 * kb + 16 * s2 + 4 * h) >> 1;
;     #pragma unroll
;                 for (int db = 0; db < 2; ++db) {
;                     const LASP unsigned* vp = Vt + (32 * db + rq) * 194 + kp;
;                     const u32x2 g0 = *(const LASP u32x2*)vp, g1 = *(const LASP u32x2*)(vp + 4);
;                     const u32x4 aw = (u32x4){g0.x, g0.y, g1.x, g1.y};
;                     oacc[db] = mfma32_g(__builtin_bit_cast(bf16x8, aw), pf, oacc[db]);
;                 }
;             }
	v_max_f32_e32 v3, v3, v3
	v_max_f32_e32 v34, v2, v3
	v_sub_f32_e32 v2, v107, v34
	v_exp_f32_e32 v6, v2
	v_sub_f32_e32 v2, v67, v34
	v_exp_f32_e32 v7, v2
	v_sub_f32_e32 v2, v68, v34
	v_exp_f32_e32 v8, v2
	v_sub_f32_e32 v3, v69, v34
	v_exp_f32_e32 v9, v3
	v_sub_f32_e32 v3, v70, v34
	v_add_f32_e32 v2, 0, v6
	v_exp_f32_e32 v10, v3
	v_sub_f32_e32 v3, v71, v34
	v_add_f32_e32 v2, v7, v2
	v_exp_f32_e32 v11, v3
	v_sub_f32_e32 v3, v72, v34
	v_add_f32_e32 v2, v8, v2
	v_exp_f32_e32 v12, v3
	v_sub_f32_e32 v3, v73, v34
	v_add_f32_e32 v2, v9, v2
	v_exp_f32_e32 v13, v3
	v_sub_f32_e32 v3, v74, v34
	v_add_f32_e32 v2, v10, v2
	v_exp_f32_e32 v67, v3
	v_sub_f32_e32 v3, v75, v34
	v_add_f32_e32 v2, v11, v2
	v_exp_f32_e32 v107, v3
	v_sub_f32_e32 v3, v76, v34
	v_add_f32_e32 v2, v12, v2
	v_exp_f32_e32 v76, v3
	v_sub_f32_e32 v3, v77, v34
	v_add_f32_e32 v2, v13, v2
	v_exp_f32_e32 v77, v3
	v_sub_f32_e32 v3, v78, v34
	v_add_f32_e32 v2, v67, v2
	v_exp_f32_e32 v78, v3
	v_sub_f32_e32 v3, v79, v34
	v_add_f32_e32 v2, v107, v2
	v_exp_f32_e32 v79, v3
	v_sub_f32_e32 v3, v80, v34
	v_add_f32_e32 v2, v76, v2
	v_exp_f32_e32 v80, v3
	v_sub_f32_e32 v3, v81, v34
	v_add_f32_e32 v2, v77, v2
	v_exp_f32_e32 v81, v3
	v_sub_f32_e32 v3, v150, v34
	v_add_f32_e32 v2, v78, v2
	v_exp_f32_e32 v150, v3
	v_sub_f32_e32 v3, v151, v34
	v_add_f32_e32 v2, v79, v2
	v_exp_f32_e32 v151, v3
	v_sub_f32_e32 v3, v152, v34
	v_add_f32_e32 v2, v80, v2
	v_exp_f32_e32 v152, v3
	v_sub_f32_e32 v3, v153, v34
	v_add_f32_e32 v2, v81, v2
	v_exp_f32_e32 v153, v3
	v_sub_f32_e32 v3, v154, v34
	v_add_f32_e32 v2, v150, v2
	v_exp_f32_e32 v154, v3
	v_sub_f32_e32 v3, v155, v34
	v_add_f32_e32 v2, v151, v2
	v_exp_f32_e32 v155, v3
	v_sub_f32_e32 v3, v156, v34
	v_add_f32_e32 v2, v152, v2
	v_exp_f32_e32 v156, v3
	v_sub_f32_e32 v3, v157, v34
	v_add_f32_e32 v2, v153, v2
	v_exp_f32_e32 v157, v3
	v_sub_f32_e32 v3, v159, v34
	v_add_f32_e32 v2, v154, v2
	v_exp_f32_e32 v159, v3
	v_sub_f32_e32 v3, v169, v34
	v_add_f32_e32 v2, v155, v2
	v_exp_f32_e32 v169, v3
	v_sub_f32_e32 v3, v224, v34
	v_add_f32_e32 v2, v156, v2
	v_exp_f32_e32 v224, v3
	v_sub_f32_e32 v3, v225, v34
	v_add_f32_e32 v2, v157, v2
	v_exp_f32_e32 v225, v3
	v_sub_f32_e32 v3, v226, v34
	v_add_f32_e32 v2, v159, v2
	v_exp_f32_e32 v226, v3
	v_sub_f32_e32 v3, v227, v34
	v_add_f32_e32 v2, v169, v2
	v_exp_f32_e32 v227, v3
	v_sub_f32_e32 v3, v228, v34
	v_add_f32_e32 v2, v224, v2
	v_exp_f32_e32 v228, v3
	v_sub_f32_e32 v3, v229, v34
	v_add_f32_e32 v2, v225, v2
	v_exp_f32_e32 v229, v3
	v_sub_f32_e32 v3, v230, v34
	v_add_f32_e32 v2, v226, v2
	v_exp_f32_e32 v230, v3
	v_sub_f32_e32 v3, v231, v34
	v_add_f32_e32 v2, v227, v2
	v_exp_f32_e32 v231, v3
	v_sub_f32_e32 v3, v232, v34
	v_add_f32_e32 v2, v228, v2
	v_exp_f32_e32 v232, v3
	v_sub_f32_e32 v3, v233, v34
	v_add_f32_e32 v2, v229, v2
	v_exp_f32_e32 v233, v3
	v_sub_f32_e32 v3, v234, v34
	v_add_f32_e32 v2, v230, v2
	v_exp_f32_e32 v234, v3
	v_sub_f32_e32 v3, v235, v34
	v_add_f32_e32 v2, v231, v2
	v_exp_f32_e32 v235, v3
	v_sub_f32_e32 v3, v236, v34
	v_add_f32_e32 v2, v232, v2
	v_exp_f32_e32 v236, v3
	v_sub_f32_e32 v3, v237, v34
	v_add_f32_e32 v2, v233, v2
	v_exp_f32_e32 v237, v3
	v_sub_f32_e32 v3, v238, v34
	v_add_f32_e32 v2, v234, v2
	v_exp_f32_e32 v238, v3
	v_sub_f32_e32 v3, v239, v34
	v_add_f32_e32 v2, v235, v2
	v_exp_f32_e32 v239, v3
	v_sub_f32_e32 v3, v240, v34
	v_add_f32_e32 v2, v236, v2
	v_exp_f32_e32 v240, v3
	v_add_f32_e32 v2, v237, v2
	v_add_f32_e32 v2, v238, v2
	v_add_f32_e32 v2, v239, v2
	v_add_f32_e32 v14, v240, v2
	v_add_u32_e32 v2, v200, v199
	v_add_u32_e32 v247, 0xc000, v2
	ds_read2_b64 v[2:5], v247 offset1:2
	v_cvt_pk_bf16_f32 v68, v6, v7
	v_cvt_pk_bf16_f32 v69, v8, v9
	v_cvt_pk_bf16_f32 v70, v10, v11
	v_cvt_pk_bf16_f32 v71, v12, v13
	v_sub_f32_e32 v15, v241, v34
	v_exp_f32_e32 v241, v15
	s_waitcnt lgkmcnt(0)
	v_mfma_f32_32x32x16_bf16 v[18:33], v[2:5], v[68:71], 0
	v_add_u32_e32 v2, v200, v201
	v_add_u32_e32 v248, 0xc000, v2
	ds_read2_b64 v[72:75], v248 offset1:2
	v_sub_f32_e32 v15, v242, v34
	v_exp_f32_e32 v242, v15
	v_sub_f32_e32 v2, v243, v34
	v_exp_f32_e32 v243, v2
	v_sub_f32_e32 v2, v244, v34
	v_exp_f32_e32 v244, v2
	v_add_f32_e32 v2, v241, v14
	v_add_f32_e32 v2, v242, v2
	v_add_f32_e32 v2, v243, v2
	v_add_f32_e32 v249, v244, v2
	s_waitcnt lgkmcnt(0)
	v_mfma_f32_32x32x16_bf16 v[2:17], v[72:75], v[68:71], 0
	ds_read2_b64 v[68:71], v247 offset0:4 offset1:6
	v_sub_f32_e32 v72, v245, v34
	v_exp_f32_e32 v245, v72
	v_sub_f32_e32 v72, v246, v34
	v_exp_f32_e32 v246, v72
	v_cvt_pk_bf16_f32 v72, v67, v107
	v_cvt_pk_bf16_f32 v73, v76, v77
	v_cvt_pk_bf16_f32 v74, v78, v79
	v_cvt_pk_bf16_f32 v75, v80, v81
	v_sub_f32_e32 v65, v65, v34
	v_exp_f32_e32 v76, v65
	s_waitcnt lgkmcnt(0)
	v_mfma_f32_32x32x16_bf16 v[18:33], v[68:71], v[72:75], v[18:33]
	ds_read2_b64 v[68:71], v248 offset0:4 offset1:6
	v_sub_f32_e32 v65, v66, v34
	v_exp_f32_e32 v77, v65
	v_add_f32_e32 v65, v245, v249
	v_add_f32_e32 v65, v246, v65
	v_add_f32_e32 v65, v76, v65
	v_add_f32_e32 v78, v77, v65
	v_add_u32_e32 v65, v202, v199
	v_add_u32_e32 v65, 0xc000, v65
	s_waitcnt lgkmcnt(0)
	v_mfma_f32_32x32x16_bf16 v[2:17], v[68:71], v[72:75], v[2:17]
	ds_read2_b64 v[66:69], v65 offset1:2
	v_sub_f32_e32 v63, v63, v34
	v_exp_f32_e32 v74, v63
	v_sub_f32_e32 v63, v64, v34
	v_exp_f32_e32 v75, v63
	v_add_u32_e32 v63, v202, v201
	v_cvt_pk_bf16_f32 v70, v150, v151
	v_cvt_pk_bf16_f32 v71, v152, v153
	v_cvt_pk_bf16_f32 v72, v154, v155
	v_cvt_pk_bf16_f32 v73, v156, v157
	v_add_u32_e32 v63, 0xc000, v63
	v_sub_f32_e32 v61, v61, v34
	s_waitcnt lgkmcnt(0)
; #define LASP __attribute__((address_space(3)))
; __device__ __forceinline__ unsigned cvtpk(float lo, float hi) { return pk2(lo, hi); }
; __device__ __forceinline__ void attn_phase_mfma(const Ctx& c, unsigned char* lds_raw, bool do_store) {
;     ...
;     #pragma unroll
;         for (int kb = 0; kb < 5; ++kb)
;     #pragma unroll
;             for (int s2 = 0; s2 < 2; ++s2) {
;                 u32x4 pw;
;     #pragma unroll
;                 for (int e = 0; e < 4; ++e) pw[e] = cvtpk(sacc[kb][8 * s2 + 2 * e], sacc[kb][8 * s2 + 2 * e + 1]);
;                 const bf16x8 pf = __builtin_bit_cast(bf16x8, pw);
;                 const int kp = (32 * wave + 32 * kb + 16 * s2 + 4 * h) >> 1;
;     #pragma unroll
;                 for (int db = 0; db < 2; ++db) {
;                     const LASP unsigned* vp = Vt + (32 * db + rq) * 194 + kp;
;                     const u32x2 g0 = *(const LASP u32x2*)vp, g1 = *(const LASP u32x2*)(vp + 4);
;                     const u32x4 aw = (u32x4){g0.x, g0.y, g1.x, g1.y};
;                     oacc[db] = mfma32_g(__builtin_bit_cast(bf16x8, aw), pf, oacc[db]);
;                 }
;             }
	v_mfma_f32_32x32x16_bf16 v[18:33], v[66:69], v[70:73], v[18:33]
	ds_read2_b64 v[64:67], v63 offset1:2
	v_exp_f32_e32 v79, v61
	v_sub_f32_e32 v61, v62, v34
	v_exp_f32_e32 v80, v61
	v_add_f32_e32 v61, v74, v78
	v_add_f32_e32 v61, v75, v61
	v_add_f32_e32 v61, v79, v61
	v_add_f32_e32 v78, v80, v61
	v_add_u32_e32 v61, v203, v199
	v_add_u32_e32 v61, 0xc000, v61
	s_waitcnt lgkmcnt(0)
	v_mfma_f32_32x32x16_bf16 v[2:17], v[64:67], v[70:73], v[2:17]
	ds_read2_b64 v[62:65], v61 offset1:2
	v_sub_f32_e32 v59, v59, v34
	v_exp_f32_e32 v70, v59
	v_sub_f32_e32 v59, v60, v34
	v_exp_f32_e32 v71, v59
	v_add_u32_e32 v59, v203, v201
	v_cvt_pk_bf16_f32 v66, v159, v169
	v_cvt_pk_bf16_f32 v67, v224, v225
	v_cvt_pk_bf16_f32 v68, v226, v227
	v_cvt_pk_bf16_f32 v69, v228, v229
	v_add_u32_e32 v59, 0xc000, v59
	v_sub_f32_e32 v57, v57, v34
	s_waitcnt lgkmcnt(0)
	v_mfma_f32_32x32x16_bf16 v[18:33], v[62:65], v[66:69], v[18:33]
	ds_read2_b64 v[60:63], v59 offset1:2
	v_exp_f32_e32 v72, v57
	v_sub_f32_e32 v57, v58, v34
	v_exp_f32_e32 v73, v57
	v_add_f32_e32 v57, v70, v78
	v_add_f32_e32 v57, v71, v57
	v_add_f32_e32 v57, v72, v57
	v_add_f32_e32 v78, v73, v57
	v_add_u32_e32 v57, v204, v199
	v_add_u32_e32 v57, 0xc000, v57
	s_waitcnt lgkmcnt(0)
	v_mfma_f32_32x32x16_bf16 v[2:17], v[60:63], v[66:69], v[2:17]
	ds_read2_b64 v[58:61], v57 offset1:2
	v_sub_f32_e32 v55, v55, v34
	v_exp_f32_e32 v66, v55
	v_sub_f32_e32 v55, v56, v34
	v_exp_f32_e32 v67, v55
	v_add_u32_e32 v55, v204, v201
	v_cvt_pk_bf16_f32 v62, v230, v231
	v_cvt_pk_bf16_f32 v63, v232, v233
	v_cvt_pk_bf16_f32 v64, v234, v235
	v_cvt_pk_bf16_f32 v65, v236, v237
	v_add_u32_e32 v55, 0xc000, v55
	v_sub_f32_e32 v53, v53, v34
	s_waitcnt lgkmcnt(0)
	v_mfma_f32_32x32x16_bf16 v[18:33], v[58:61], v[62:65], v[18:33]
	ds_read2_b64 v[56:59], v55 offset1:2
	v_exp_f32_e32 v68, v53
	v_sub_f32_e32 v53, v54, v34
	v_exp_f32_e32 v69, v53
	v_add_f32_e32 v53, v66, v78
	v_add_f32_e32 v53, v67, v53
	v_add_f32_e32 v53, v68, v53
	v_add_f32_e32 v78, v69, v53
	v_add_u32_e32 v53, v205, v199
	v_add_u32_e32 v53, 0xc000, v53
	s_waitcnt lgkmcnt(0)
	v_mfma_f32_32x32x16_bf16 v[2:17], v[56:59], v[62:65], v[2:17]
	ds_read2_b64 v[54:57], v53 offset1:2
	v_sub_f32_e32 v51, v51, v34
	v_exp_f32_e32 v62, v51
	v_sub_f32_e32 v51, v52, v34
	v_exp_f32_e32 v63, v51
	v_add_u32_e32 v51, v205, v201
	v_cvt_pk_bf16_f32 v58, v238, v239
	v_cvt_pk_bf16_f32 v59, v240, v241
	v_cvt_pk_bf16_f32 v60, v242, v243
	v_cvt_pk_bf16_f32 v61, v244, v245
	v_add_u32_e32 v51, 0xc000, v51
	v_sub_f32_e32 v49, v49, v34
	s_waitcnt lgkmcnt(0)
	v_mfma_f32_32x32x16_bf16 v[18:33], v[54:57], v[58:61], v[18:33]
	ds_read2_b64 v[52:55], v51 offset1:2
	v_exp_f32_e32 v64, v49
	v_sub_f32_e32 v49, v50, v34
	v_exp_f32_e32 v65, v49
	v_add_f32_e32 v49, v62, v78
	v_add_f32_e32 v49, v63, v49
	v_add_f32_e32 v49, v64, v49
	v_add_f32_e32 v78, v65, v49
	v_add_u32_e32 v49, v206, v199
	v_add_u32_e32 v49, 0xc000, v49
	s_waitcnt lgkmcnt(0)
	v_mfma_f32_32x32x16_bf16 v[2:17], v[52:55], v[58:61], v[2:17]
	ds_read2_b64 v[50:53], v49 offset1:2
	v_sub_f32_e32 v47, v47, v34
	v_exp_f32_e32 v58, v47
	v_sub_f32_e32 v47, v48, v34
	v_exp_f32_e32 v59, v47
	v_add_u32_e32 v47, v206, v201
	v_cvt_pk_bf16_f32 v54, v246, v76
	v_cvt_pk_bf16_f32 v55, v77, v74
	v_cvt_pk_bf16_f32 v56, v75, v79
	v_cvt_pk_bf16_f32 v57, v80, v70
	v_add_u32_e32 v47, 0xc000, v47
	v_sub_f32_e32 v45, v45, v34
	s_waitcnt lgkmcnt(0)
	v_mfma_f32_32x32x16_bf16 v[18:33], v[50:53], v[54:57], v[18:33]
	ds_read2_b64 v[48:51], v47 offset1:2
	v_exp_f32_e32 v60, v45
	v_sub_f32_e32 v45, v46, v34
	v_exp_f32_e32 v61, v45
	v_add_f32_e32 v45, v58, v78
	v_add_f32_e32 v45, v59, v45
	v_add_f32_e32 v45, v60, v45
	v_add_f32_e32 v70, v61, v45
	v_add_u32_e32 v45, v207, v199
	v_add_u32_e32 v45, 0xc000, v45
	s_waitcnt lgkmcnt(0)
	v_mfma_f32_32x32x16_bf16 v[2:17], v[48:51], v[54:57], v[2:17]
	ds_read2_b64 v[46:49], v45 offset1:2
	v_sub_f32_e32 v43, v43, v34
	v_exp_f32_e32 v54, v43
	v_sub_f32_e32 v43, v44, v34
	v_exp_f32_e32 v55, v43
	v_add_u32_e32 v43, v207, v201
	v_cvt_pk_bf16_f32 v50, v71, v72
	v_cvt_pk_bf16_f32 v51, v73, v66
	v_cvt_pk_bf16_f32 v52, v67, v68
	v_cvt_pk_bf16_f32 v53, v69, v62
	v_add_u32_e32 v43, 0xc000, v43
	v_sub_f32_e32 v41, v41, v34
	s_waitcnt lgkmcnt(0)
	v_mfma_f32_32x32x16_bf16 v[18:33], v[46:49], v[50:53], v[18:33]
	ds_read2_b64 v[44:47], v43 offset1:2
	v_exp_f32_e32 v56, v41
	v_sub_f32_e32 v41, v42, v34
	v_exp_f32_e32 v57, v41
	v_add_f32_e32 v41, v54, v70
	v_add_f32_e32 v41, v55, v41
	v_add_f32_e32 v41, v56, v41
	v_add_f32_e32 v62, v57, v41
	v_add_u32_e32 v41, v208, v199
	v_add_u32_e32 v41, 0xc000, v41
	s_waitcnt lgkmcnt(0)
; __device__ __forceinline__ unsigned cvtpk(float lo, float hi) { return pk2(lo, hi); }
; __device__ __forceinline__ void attn_phase_mfma(const Ctx& c, unsigned char* lds_raw, bool do_store) {
;     ...
;         if (do_store) {
;             const float inv = 1.f / lsum;
;     #pragma unroll
;             for (int db = 0; db < 2; ++db)
;     #pragma unroll
;                 for (int g4 = 0; g4 < 4; ++g4) {
;                     const u32x2 w = (u32x2){cvtpk(oacc[db][4 * g4] * inv, oacc[db][4 * g4 + 1] * inv), cvtpk(oacc[db][4 * g4 + 2] * inv, oacc[db][4 * g4 + 3] * inv)};
;                     *(u32x2*)(qrow + 32 * db + 8 * g4 + 4 * h) = w;
;                 }
	v_mfma_f32_32x32x16_bf16 v[2:17], v[44:47], v[50:53], v[2:17]
	ds_read2_b64 v[42:45], v41 offset1:2
	v_sub_f32_e32 v39, v39, v34
	v_exp_f32_e32 v50, v39
	v_sub_f32_e32 v39, v40, v34
	v_exp_f32_e32 v51, v39
	v_add_u32_e32 v39, v208, v201
	v_cvt_pk_bf16_f32 v46, v63, v64
	v_cvt_pk_bf16_f32 v47, v65, v58
	v_cvt_pk_bf16_f32 v48, v59, v60
	v_cvt_pk_bf16_f32 v49, v61, v54
	v_add_u32_e32 v39, 0xc000, v39
	v_sub_f32_e32 v36, v36, v34
	s_waitcnt lgkmcnt(0)
	v_mfma_f32_32x32x16_bf16 v[18:33], v[42:45], v[46:49], v[18:33]
	ds_read2_b64 v[40:43], v39 offset1:2
	v_exp_f32_e32 v45, v36
	v_sub_f32_e32 v36, v37, v34
	v_exp_f32_e32 v52, v36
	v_sub_f32_e32 v36, v38, v34
	v_exp_f32_e32 v53, v36
	v_add_u32_e32 v36, v209, v199
	v_add_f32_e32 v39, v50, v62
	v_add_u32_e32 v36, 0xc000, v36
	v_add_f32_e32 v44, v51, v39
	s_waitcnt lgkmcnt(0)
	v_mfma_f32_32x32x16_bf16 v[2:17], v[40:43], v[46:49], v[2:17]
	ds_read2_b64 v[36:39], v36 offset1:2
	v_add_f32_e32 v40, v45, v44
	v_add_f32_e32 v40, v52, v40
	v_add_f32_e32 v44, v53, v40
	v_cvt_pk_bf16_f32 v40, v55, v56
	v_cvt_pk_bf16_f32 v41, v57, v50
	v_cvt_pk_bf16_f32 v42, v51, v45
	v_cvt_pk_bf16_f32 v43, v52, v53
	ds_bpermute_b32 v35, v35, v44
	s_waitcnt lgkmcnt(0)
	v_add_f32_e32 v35, v44, v35
	v_mfma_f32_32x32x16_bf16 v[18:33], v[36:39], v[40:43], v[18:33]
	v_add_u32_e32 v36, v209, v201
	v_add_u32_e32 v36, 0xc000, v36
	ds_read2_b64 v[36:39], v36 offset1:2
	v_div_scale_f32 v44, s[0:1], v35, v35, 1.0
	v_rcp_f32_e32 v45, v44
	s_waitcnt lgkmcnt(0)
	v_mfma_f32_32x32x16_bf16 v[2:17], v[36:39], v[40:43], v[2:17]
	v_fma_f32 v36, -v44, v45, 1.0
	v_fmac_f32_e32 v45, v36, v45
	v_div_scale_f32 v36, vcc, 1.0, v35, 1.0
	v_mul_f32_e32 v37, v36, v45
	v_fma_f32 v38, -v44, v37, v36
	v_fmac_f32_e32 v37, v38, v45
	v_fma_f32 v36, -v44, v37, v36
	v_div_fmas_f32 v36, v36, v45, v37
	s_nop 15
	s_nop 15
	v_div_fixup_f32 v36, v36, v35, 1.0
	v_lshlrev_b32_e32 v38, 1, v166
	v_and_b32_e32 v39, 32, v0
	v_lshrrev_b32_e32 v39, 2, v39
	v_add_u32_e32 v38, v38, v39
	v_mov_b32_e32 v39, v106
	v_lshl_add_u64 v[38:39], v[174:175], 0, v[38:39]
	v_pk_mul_f32 v[18:19], v[18:19], v[36:37] op_sel_hi:[1,0]
	v_pk_mul_f32 v[20:21], v[20:21], v[36:37] op_sel_hi:[1,0]
	v_cvt_pk_bf16_f32 v18, v18, v19
	v_cvt_pk_bf16_f32 v19, v20, v21
	v_pk_mul_f32 v[20:21], v[22:23], v[36:37] op_sel_hi:[1,0]
	v_pk_mul_f32 v[22:23], v[24:25], v[36:37] op_sel_hi:[1,0]
	v_cvt_pk_bf16_f32 v20, v20, v21
	v_cvt_pk_bf16_f32 v21, v22, v23
	v_pk_mul_f32 v[2:3], v[2:3], v[36:37] op_sel_hi:[1,0]
	v_pk_mul_f32 v[4:5], v[4:5], v[36:37] op_sel_hi:[1,0]
	v_permlane32_swap_b32_e32 v18, v20
	v_permlane32_swap_b32_e32 v19, v21
	v_cvt_pk_bf16_f32 v2, v2, v3
	v_cvt_pk_bf16_f32 v3, v4, v5
	v_pk_mul_f32 v[4:5], v[6:7], v[36:37] op_sel_hi:[1,0]
	v_pk_mul_f32 v[6:7], v[8:9], v[36:37] op_sel_hi:[1,0]
	global_store_dwordx4 v[38:39], v[18:21], off offset:1536
	v_cvt_pk_bf16_f32 v4, v4, v5
	v_cvt_pk_bf16_f32 v5, v6, v7
	v_pk_mul_f32 v[22:23], v[26:27], v[36:37] op_sel_hi:[1,0]
	v_pk_mul_f32 v[24:25], v[28:29], v[36:37] op_sel_hi:[1,0]
	v_permlane32_swap_b32_e32 v2, v4
	v_permlane32_swap_b32_e32 v3, v5
	v_cvt_pk_bf16_f32 v22, v22, v23
	v_cvt_pk_bf16_f32 v23, v24, v25
	v_pk_mul_f32 v[24:25], v[30:31], v[36:37] op_sel_hi:[1,0]
	v_pk_mul_f32 v[26:27], v[32:33], v[36:37] op_sel_hi:[1,0]
	global_store_dwordx4 v[38:39], v[2:5], off offset:1600
	v_cvt_pk_bf16_f32 v24, v24, v25
	v_cvt_pk_bf16_f32 v25, v26, v27
	v_pk_mul_f32 v[6:7], v[10:11], v[36:37] op_sel_hi:[1,0]
	v_pk_mul_f32 v[8:9], v[12:13], v[36:37] op_sel_hi:[1,0]
	v_permlane32_swap_b32_e32 v22, v24
	v_permlane32_swap_b32_e32 v23, v25
	v_cvt_pk_bf16_f32 v6, v6, v7
	v_cvt_pk_bf16_f32 v7, v8, v9
	v_pk_mul_f32 v[8:9], v[14:15], v[36:37] op_sel_hi:[1,0]
	v_pk_mul_f32 v[10:11], v[16:17], v[36:37] op_sel_hi:[1,0]
	global_store_dwordx4 v[38:39], v[22:25], off offset:1568
	v_cvt_pk_bf16_f32 v8, v8, v9
	v_cvt_pk_bf16_f32 v9, v10, v11
	s_nop 1
	v_permlane32_swap_b32_e32 v6, v8
	v_permlane32_swap_b32_e32 v7, v9
	global_store_dwordx4 v[38:39], v[6:9], off offset:1632
	s_mov_b64 s[0:1], exec
	v_readlane_b32 s10, v255, 15
	v_readlane_b32 s11, v255, 16
	s_and_b64 s[10:11], s[0:1], s[10:11]
	s_mov_b64 exec, s[10:11]
	s_cbranch_execz .LBB0_1718
	s_mov_b32 s3, 0x800000
	v_cmp_gt_f32_e32 vcc, s3, v35
	s_mov_b32 s3, 0x3f317217
	s_ashr_i32 s89, s88, 31
	v_cndmask_b32_e64 v2, 0, 32, vcc
	v_ldexp_f32 v2, v35, v2
	v_log_f32_e32 v2, v2
	v_cndmask_b32_e32 v3, 0, v223, vcc
	s_lshl_b64 s[10:11], s[88:89], 19
	v_mul_f32_e32 v4, 0x3f317217, v2
	v_fma_f32 v4, v2, s3, -v4
	s_mov_b32 s3, 0x7f800000
	v_fmac_f32_e32 v4, 0x3377d1cf, v2
	v_cmp_lt_f32_e64 vcc, |v2|, s3
	v_readlane_b32 s3, v255, 13
	v_fmac_f32_e32 v4, 0x3f317217, v2
	s_add_u32 s10, s3, s10
	v_readlane_b32 s3, v255, 14
	v_cndmask_b32_e32 v2, v2, v4, vcc
	s_addc_u32 s11, s3, s11
	v_sub_f32_e32 v4, v2, v3
	v_lshl_add_u64 v[2:3], v[108:109], 4, s[10:11]
	s_lshl_b32 s96, s2, 2
	v_fmac_f32_e32 v4, 0x3f317218, v34
	v_lshl_add_u64 v[2:3], v[2:3], 0, s[96:97]
	global_store_dword v[2:3], v4, off
	s_branch .LBB0_1718
